# v33 + attention loops: redundant self-max canonicalisation pairs after the row-max lane swap removed (9 sites, value-identical)
# baseline (speedup 1.0000x reference)
.LBB0_787:
	v_add_u32_e32 v180, s10, v229
	ds_read_b64_tr_b16 v[176:177], v180 offset:24576
	ds_read_b64_tr_b16 v[178:179], v180 offset:25088
	v_add_f32_e32 v80, v64, v65
	v_add_f32_e32 v80, v66, v80
	v_add_f32_e32 v80, v67, v80
	v_add_f32_e32 v80, v68, v80
	v_add_f32_e32 v96, v69, v80
	v_mfma_f32_32x32x16_bf16 v[80:95], v[172:175], v[128:131], v[32:47]
	v_cvt_pk_bf16_f32 v140, v64, v65
	v_cvt_pk_bf16_f32 v141, v66, v67
	ds_read_b64_tr_b16 v[172:173], v180 offset:28672
	ds_read_b64_tr_b16 v[174:175], v180 offset:29184
	v_add_f32_e32 v64, v70, v96
	v_add_f32_e32 v64, v71, v64
	v_add_f32_e32 v64, v72, v64
	v_add_f32_e32 v64, v73, v64
	v_cvt_pk_bf16_f32 v142, v68, v69
	v_cvt_pk_bf16_f32 v143, v70, v71
	v_mfma_f32_32x32x16_bf16 v[96:111], v[168:171], v[128:131], v[32:47]
	ds_read_b64_tr_b16 v[168:169], v180 offset:25600
	ds_read_b64_tr_b16 v[170:171], v180 offset:26112
	v_mfma_f32_32x32x16_bf16 v[80:95], v[164:167], v[120:123], v[80:95]
	v_add_f32_e32 v64, v74, v64
	v_add_f32_e32 v64, v75, v64
	v_add_f32_e32 v64, v76, v64
	v_add_f32_e32 v64, v77, v64
	v_cvt_pk_bf16_f32 v136, v72, v73
	v_cvt_pk_bf16_f32 v137, v74, v75
	ds_read_b64_tr_b16 v[164:165], v180 offset:29696
	ds_read_b64_tr_b16 v[166:167], v180 offset:30208
	v_add_f32_e32 v64, v78, v64
	v_add_f32_e32 v64, v79, v64
	v_add_f32_e32 v64, v48, v64
	v_add_f32_e32 v64, v49, v64
	v_cvt_pk_bf16_f32 v138, v76, v77
	v_cvt_pk_bf16_f32 v139, v78, v79
	v_mfma_f32_32x32x16_bf16 v[96:111], v[160:163], v[120:123], v[96:111]
	ds_read_b64_tr_b16 v[160:161], v180 offset:26624
	ds_read_b64_tr_b16 v[162:163], v180 offset:27136
	v_mfma_f32_32x32x16_bf16 v[80:95], v[156:159], v[116:119], v[80:95]
	v_add_f32_e32 v64, v50, v64
	v_add_f32_e32 v64, v51, v64
	v_add_f32_e32 v64, v52, v64
	v_add_f32_e32 v64, v53, v64
	v_cvt_pk_bf16_f32 v132, v48, v49
	v_cvt_pk_bf16_f32 v133, v50, v51
	ds_read_b64_tr_b16 v[156:157], v180 offset:30720
	ds_read_b64_tr_b16 v[158:159], v180 offset:31232
	v_add_f32_e32 v48, v54, v64
	v_add_f32_e32 v48, v55, v48
	v_add_f32_e32 v48, v56, v48
	v_add_f32_e32 v48, v57, v48
	v_cvt_pk_bf16_f32 v134, v52, v53
	v_cvt_pk_bf16_f32 v135, v54, v55
	v_mfma_f32_32x32x16_bf16 v[96:111], v[152:155], v[116:119], v[96:111]
	ds_read_b64_tr_b16 v[152:153], v180 offset:27648
	ds_read_b64_tr_b16 v[154:155], v180 offset:28160
	v_mfma_f32_32x32x16_bf16 v[80:95], v[148:151], v[112:115], v[80:95]
	v_add_f32_e32 v48, v58, v48
	v_add_f32_e32 v48, v59, v48
	v_add_f32_e32 v48, v60, v48
	v_add_f32_e32 v48, v61, v48
	v_cvt_pk_bf16_f32 v124, v56, v57
	v_cvt_pk_bf16_f32 v125, v58, v59
	ds_read_b64_tr_b16 v[148:149], v180 offset:31744
	ds_read_b64_tr_b16 v[150:151], v180 offset:32256
	v_add_f32_e32 v48, v62, v48
	v_add_f32_e32 v48, v63, v48
	v_add_f32_e32 v180, 0, v48
	v_cvt_pk_bf16_f32 v126, v60, v61
	v_cvt_pk_bf16_f32 v127, v62, v63
	v_mfma_f32_32x32x16_bf16 v[96:111], v[144:147], v[112:115], v[96:111]
	s_waitcnt lgkmcnt(8)
	ds_read_b128 v[64:67], v196
	ds_read_b128 v[68:71], v196 offset:32
	ds_read_b128 v[72:75], v196 offset:64
	ds_read_b128 v[76:79], v196 offset:96
	ds_read_b128 v[52:55], v196 offset:160
	ds_read_b128 v[56:59], v196 offset:192
	ds_read_b128 v[60:63], v196 offset:224
	v_lshl_add_u64 v[48:49], v[194:195], 0, s[24:25]
	s_add_i32 s0, s36, s65
	s_mov_b32 m0, s0
	s_nop 0
	global_load_lds_dwordx4 v[48:49], off
	v_lshl_add_u64 v[48:49], v[192:193], 0, s[24:25]
	s_add_i32 s0, s1, s68
	s_mov_b32 m0, s0
	s_nop 0
	global_load_lds_dwordx4 v[48:49], off
	ds_read_b128 v[48:51], v196 offset:128
	s_waitcnt lgkmcnt(4)
	v_add_f32_e32 v64, v80, v64
	v_add_f32_e32 v65, v81, v65
	v_add_f32_e32 v66, v82, v66
	v_add_f32_e32 v67, v83, v67
	v_add_f32_e32 v68, v84, v68
	v_add_f32_e32 v69, v85, v69
	v_add_f32_e32 v70, v86, v70
	v_add_f32_e32 v71, v87, v71
	v_add_f32_e32 v72, v88, v72
	v_add_f32_e32 v73, v89, v73
	v_add_f32_e32 v74, v90, v74
	v_add_f32_e32 v75, v91, v75
	v_add_f32_e32 v76, v92, v76
	v_add_f32_e32 v77, v93, v77
	v_add_f32_e32 v78, v94, v78
	v_add_f32_e32 v79, v95, v79
	s_waitcnt lgkmcnt(1)
	v_add_f32_e32 v52, v100, v52
	v_add_f32_e32 v53, v101, v53
	v_add_f32_e32 v54, v102, v54
	v_add_f32_e32 v55, v103, v55
	v_add_f32_e32 v56, v104, v56
	v_add_f32_e32 v57, v105, v57
	v_add_f32_e32 v58, v106, v58
	v_add_f32_e32 v59, v107, v59
	v_add_f32_e32 v60, v108, v60
	v_add_f32_e32 v61, v109, v61
	v_add_f32_e32 v62, v110, v62
	v_add_f32_e32 v63, v111, v63
	s_waitcnt lgkmcnt(0)
	v_add_f32_e32 v48, v96, v48
	v_add_f32_e32 v49, v97, v49
	v_add_f32_e32 v50, v98, v50
	v_add_f32_e32 v51, v99, v51
	v_max_f32_e32 v80, v64, v65
	v_max3_f32 v81, v66, v67, v49
	v_max3_f32 v80, v80, v48, v50
	v_max3_f32 v80, v80, v51, v68
	v_max3_f32 v81, v81, v70, v71
	v_max3_f32 v80, v80, v69, v52
	v_max3_f32 v81, v81, v54, v55
	v_max3_f32 v80, v80, v53, v72
	v_max3_f32 v81, v81, v74, v75
	v_max3_f32 v80, v80, v73, v56
	v_max3_f32 v81, v81, v58, v59
	v_max3_f32 v80, v80, v57, v76
	v_max3_f32 v81, v81, v78, v79
	v_max3_f32 v80, v80, v77, v60
	v_max3_f32 v81, v81, v62, v63
	v_max3_f32 v80, v80, v61, v81
	v_mov_b32_e32 v81, v80
	s_nop 1
	v_permlane32_swap_b32_e32 v80, v81
	v_max_f32_e32 v80, v80, v81
	v_cmp_lt_f32_e32 vcc, s61, v80
	s_cmp_lg_u64 vcc, 0
	v_add_f32_e32 v197, v231, v180
	s_cselect_b64 s[10:11], -1, 0
	s_cbranch_vccnz .LBB0_795

.LBB0_790:
	s_add_i32 s0, s1, 0x2000
	s_cmpk_lg_i32 s1, 0x4000
	s_cselect_b32 s71, s0, 0
	v_add_u32_e32 v198, s36, v229
	ds_read_b64_tr_b16 v[160:161], v198 offset:24576
	ds_read_b64_tr_b16 v[162:163], v198 offset:25088
	v_add_f32_e32 v80, v64, v65
	v_add_f32_e32 v80, v66, v80
	v_add_f32_e32 v80, v67, v80
	v_add_f32_e32 v80, v68, v80
	v_add_f32_e32 v100, v69, v80
	v_mfma_f32_32x32x16_bf16 v[80:95], v[96:99], v[128:131], v[32:47]
	v_cvt_pk_bf16_f32 v140, v64, v65
	v_cvt_pk_bf16_f32 v141, v66, v67
	ds_read_b64_tr_b16 v[156:157], v198 offset:28672
	ds_read_b64_tr_b16 v[158:159], v198 offset:29184
	v_add_f32_e32 v64, v70, v100
	v_add_f32_e32 v64, v71, v64
	v_add_f32_e32 v64, v72, v64
	v_add_f32_e32 v64, v73, v64
	v_cvt_pk_bf16_f32 v142, v68, v69
	v_cvt_pk_bf16_f32 v143, v70, v71
	v_mfma_f32_32x32x16_bf16 v[96:111], v[180:183], v[128:131], v[32:47]
	ds_read_b64_tr_b16 v[152:153], v198 offset:25600
	ds_read_b64_tr_b16 v[154:155], v198 offset:26112
	v_mfma_f32_32x32x16_bf16 v[80:95], v[184:187], v[120:123], v[80:95]
	v_add_f32_e32 v64, v74, v64
	v_add_f32_e32 v64, v75, v64
	v_add_f32_e32 v64, v76, v64
	v_add_f32_e32 v64, v77, v64
	v_cvt_pk_bf16_f32 v136, v72, v73
	v_cvt_pk_bf16_f32 v137, v74, v75
	ds_read_b64_tr_b16 v[148:149], v198 offset:29696
	ds_read_b64_tr_b16 v[150:151], v198 offset:30208
	v_add_f32_e32 v64, v78, v64
	v_add_f32_e32 v64, v79, v64
	v_add_f32_e32 v64, v48, v64
	v_add_f32_e32 v64, v49, v64
	v_cvt_pk_bf16_f32 v138, v76, v77
	v_cvt_pk_bf16_f32 v139, v78, v79
	v_mfma_f32_32x32x16_bf16 v[96:111], v[144:147], v[120:123], v[96:111]
	ds_read_b64_tr_b16 v[144:145], v198 offset:26624
	ds_read_b64_tr_b16 v[146:147], v198 offset:27136
	v_mfma_f32_32x32x16_bf16 v[80:95], v[176:179], v[116:119], v[80:95]
	v_add_f32_e32 v64, v50, v64
	v_add_f32_e32 v64, v51, v64
	v_add_f32_e32 v64, v52, v64
	v_add_f32_e32 v64, v53, v64
	v_cvt_pk_bf16_f32 v132, v48, v49
	v_cvt_pk_bf16_f32 v133, v50, v51
	ds_read_b64_tr_b16 v[184:185], v198 offset:30720
	ds_read_b64_tr_b16 v[186:187], v198 offset:31232
	v_add_f32_e32 v48, v54, v64
	v_add_f32_e32 v48, v55, v48
	v_add_f32_e32 v48, v56, v48
	v_add_f32_e32 v48, v57, v48
	v_cvt_pk_bf16_f32 v134, v52, v53
	v_cvt_pk_bf16_f32 v135, v54, v55
	v_mfma_f32_32x32x16_bf16 v[96:111], v[168:171], v[116:119], v[96:111]
	ds_read_b64_tr_b16 v[180:181], v198 offset:27648
	ds_read_b64_tr_b16 v[182:183], v198 offset:28160
	v_mfma_f32_32x32x16_bf16 v[80:95], v[172:175], v[112:115], v[80:95]
	v_add_f32_e32 v48, v58, v48
	v_add_f32_e32 v48, v59, v48
	v_add_f32_e32 v48, v60, v48
	v_add_f32_e32 v48, v61, v48
	v_cvt_pk_bf16_f32 v124, v56, v57
	v_cvt_pk_bf16_f32 v125, v58, v59
	ds_read_b64_tr_b16 v[176:177], v198 offset:31744
	ds_read_b64_tr_b16 v[178:179], v198 offset:32256
	v_add_f32_e32 v48, v62, v48
	v_add_f32_e32 v48, v63, v48
	v_add_f32_e32 v168, 0, v48
	v_cvt_pk_bf16_f32 v126, v60, v61
	v_cvt_pk_bf16_f32 v127, v62, v63
	v_mfma_f32_32x32x16_bf16 v[96:111], v[164:167], v[112:115], v[96:111]
	s_waitcnt lgkmcnt(8)
	ds_read_b128 v[64:67], v196 offset:256
	ds_read_b128 v[68:71], v196 offset:288
	ds_read_b128 v[72:75], v196 offset:320
	ds_read_b128 v[76:79], v196 offset:352
	ds_read_b128 v[48:51], v196 offset:384
	ds_read_b128 v[52:55], v196 offset:416
	ds_read_b128 v[56:59], v196 offset:448
	ds_read_b128 v[60:63], v196 offset:480
	s_add_i32 s0, s1, s65
	s_mov_b32 m0, s0
	s_nop 0
	global_load_lds_dwordx4 v[194:195], off
	s_add_i32 s0, s71, s68
	s_mov_b32 m0, s0
	s_nop 0
	global_load_lds_dwordx4 v[192:193], off
	s_waitcnt lgkmcnt(4)
	v_add_f32_e32 v64, v80, v64
	v_add_f32_e32 v65, v81, v65
	v_add_f32_e32 v66, v82, v66
	v_add_f32_e32 v67, v83, v67
	v_add_f32_e32 v68, v84, v68
	v_add_f32_e32 v69, v85, v69
	v_add_f32_e32 v70, v86, v70
	v_add_f32_e32 v71, v87, v71
	v_add_f32_e32 v72, v88, v72
	v_add_f32_e32 v73, v89, v73
	v_add_f32_e32 v74, v90, v74
	v_add_f32_e32 v75, v91, v75
	v_add_f32_e32 v76, v92, v76
	v_add_f32_e32 v77, v93, v77
	v_add_f32_e32 v78, v94, v78
	v_add_f32_e32 v79, v95, v79
	s_waitcnt lgkmcnt(1)
	v_add_f32_e32 v48, v96, v48
	v_add_f32_e32 v49, v97, v49
	v_add_f32_e32 v50, v98, v50
	v_add_f32_e32 v51, v99, v51
	v_add_f32_e32 v52, v100, v52
	v_add_f32_e32 v53, v101, v53
	v_add_f32_e32 v54, v102, v54
	v_add_f32_e32 v55, v103, v55
	v_add_f32_e32 v56, v104, v56
	v_add_f32_e32 v57, v105, v57
	v_add_f32_e32 v58, v106, v58
	v_add_f32_e32 v59, v107, v59
	s_waitcnt lgkmcnt(0)
	v_add_f32_e32 v60, v108, v60
	v_add_f32_e32 v61, v109, v61
	v_add_f32_e32 v62, v110, v62
	v_add_f32_e32 v63, v111, v63
	v_max_f32_e32 v80, v64, v65
	v_max3_f32 v81, v66, v67, v49
	v_max3_f32 v80, v80, v48, v50
	v_max3_f32 v80, v80, v51, v68
	v_max3_f32 v81, v81, v70, v71
	v_max3_f32 v80, v80, v69, v52
	v_max3_f32 v81, v81, v54, v55
	v_max3_f32 v80, v80, v53, v72
	v_max3_f32 v81, v81, v74, v75
	v_max3_f32 v80, v80, v73, v56
	v_max3_f32 v81, v81, v58, v59
	v_max3_f32 v80, v80, v57, v76
	v_max3_f32 v81, v81, v78, v79
	v_max3_f32 v80, v80, v77, v60
	v_max3_f32 v81, v81, v62, v63
	v_max3_f32 v80, v80, v61, v81
	v_mov_b32_e32 v81, v80
	s_nop 1
	v_permlane32_swap_b32_e32 v80, v81
	v_max_f32_e32 v80, v80, v81
	v_cmp_lt_f32_e32 vcc, s61, v80
	s_cmp_lg_u64 vcc, 0
	v_add_f32_e32 v231, v197, v168
	s_cselect_b64 s[10:11], -1, 0
	s_cbranch_vccnz .LBB0_798

.LBB0_803:
	v_add_u32_e32 v98, s0, v229
	ds_read_b64_tr_b16 v[176:177], v98 offset:24576
	ds_read_b64_tr_b16 v[178:179], v98 offset:25088
	v_add_f32_e32 v80, v64, v65
	v_add_f32_e32 v80, v66, v80
	v_add_f32_e32 v80, v67, v80
	v_add_f32_e32 v80, v68, v80
	v_add_f32_e32 v96, v69, v80
	s_waitcnt lgkmcnt(3)
	v_mfma_f32_32x32x16_bf16 v[80:95], v[172:175], v[128:131], v[32:47]
	v_cvt_pk_bf16_f32 v140, v64, v65
	v_cvt_pk_bf16_f32 v141, v66, v67
	ds_read_b64_tr_b16 v[172:173], v98 offset:28672
	ds_read_b64_tr_b16 v[174:175], v98 offset:29184
	s_waitcnt lgkmcnt(4)
	v_mfma_f32_32x32x16_bf16 v[32:47], v[168:171], v[128:131], v[32:47]
	v_add_f32_e32 v64, v70, v96
	v_add_f32_e32 v64, v71, v64
	v_add_f32_e32 v64, v72, v64
	v_add_f32_e32 v64, v73, v64
	v_cvt_pk_bf16_f32 v142, v68, v69
	v_cvt_pk_bf16_f32 v143, v70, v71
	ds_read_b64_tr_b16 v[168:169], v98 offset:25600
	ds_read_b64_tr_b16 v[170:171], v98 offset:26112
	v_mfma_f32_32x32x16_bf16 v[80:95], v[164:167], v[120:123], v[80:95]
	v_add_f32_e32 v64, v74, v64
	v_add_f32_e32 v64, v75, v64
	v_add_f32_e32 v64, v76, v64
	v_add_f32_e32 v64, v77, v64
	v_cvt_pk_bf16_f32 v136, v72, v73
	v_cvt_pk_bf16_f32 v137, v74, v75
	ds_read_b64_tr_b16 v[128:129], v98 offset:29696
	ds_read_b64_tr_b16 v[130:131], v98 offset:30208
	v_mfma_f32_32x32x16_bf16 v[32:47], v[160:163], v[120:123], v[32:47]
	v_add_f32_e32 v64, v78, v64
	v_add_f32_e32 v64, v79, v64
	v_add_f32_e32 v64, v48, v64
	v_add_f32_e32 v64, v49, v64
	v_cvt_pk_bf16_f32 v138, v76, v77
	v_cvt_pk_bf16_f32 v139, v78, v79
	ds_read_b64_tr_b16 v[108:109], v98 offset:26624
	ds_read_b64_tr_b16 v[110:111], v98 offset:27136
	v_mfma_f32_32x32x16_bf16 v[80:95], v[156:159], v[116:119], v[80:95]
	v_add_f32_e32 v64, v50, v64
	v_add_f32_e32 v64, v51, v64
	v_add_f32_e32 v64, v52, v64
	v_add_f32_e32 v64, v53, v64
	v_cvt_pk_bf16_f32 v132, v48, v49
	v_cvt_pk_bf16_f32 v133, v50, v51
	ds_read_b64_tr_b16 v[104:105], v98 offset:30720
	ds_read_b64_tr_b16 v[106:107], v98 offset:31232
	v_mfma_f32_32x32x16_bf16 v[32:47], v[152:155], v[116:119], v[32:47]
	v_add_f32_e32 v48, v54, v64
	v_add_f32_e32 v48, v55, v48
	v_add_f32_e32 v48, v56, v48
	v_add_f32_e32 v48, v57, v48
	v_cvt_pk_bf16_f32 v134, v52, v53
	v_cvt_pk_bf16_f32 v135, v54, v55
	ds_read_b64_tr_b16 v[100:101], v98 offset:27648
	ds_read_b64_tr_b16 v[102:103], v98 offset:28160
	v_mfma_f32_32x32x16_bf16 v[80:95], v[148:151], v[112:115], v[80:95]
	v_add_f32_e32 v48, v58, v48
	v_add_f32_e32 v48, v59, v48
	v_add_f32_e32 v48, v60, v48
	v_add_f32_e32 v48, v61, v48
	v_cvt_pk_bf16_f32 v124, v56, v57
	v_cvt_pk_bf16_f32 v125, v58, v59
	ds_read_b64_tr_b16 v[96:97], v98 offset:31744
	ds_read_b64_tr_b16 v[98:99], v98 offset:32256
	v_mfma_f32_32x32x16_bf16 v[32:47], v[144:147], v[112:115], v[32:47]
	v_add_f32_e32 v48, v62, v48
	v_add_f32_e32 v48, v63, v48
	v_add_f32_e32 v116, 0, v48
	v_cvt_pk_bf16_f32 v126, v60, v61
	v_cvt_pk_bf16_f32 v127, v62, v63
	s_lshl_b32 s0, s69, 2
	s_add_i32 s0, s0, 0
	s_add_i32 s0, s0, 0x15000
	v_lshl_add_u32 v48, v225, 2, s0
	v_add_u32_e32 v76, 0xffffff00, v48
	ds_read_b128 v[48:51], v76
	ds_read_b128 v[52:55], v76 offset:128
	ds_read_b128 v[56:59], v76 offset:32
	ds_read_b128 v[60:63], v76 offset:160
	ds_read_b128 v[64:67], v76 offset:64
	ds_read_b128 v[68:71], v76 offset:192
	ds_read_b128 v[72:75], v76 offset:96
	ds_read_b128 v[76:79], v76 offset:224
	s_waitcnt lgkmcnt(7)
	v_add_f32_e32 v50, v82, v50
	v_add_f32_e32 v51, v83, v51
	s_waitcnt lgkmcnt(5)
	v_add_f32_e32 v56, v84, v56
	v_add_f32_e32 v57, v85, v57
	v_add_f32_e32 v58, v86, v58
	v_add_f32_e32 v59, v87, v59
	s_waitcnt lgkmcnt(3)
	v_add_f32_e32 v64, v88, v64
	v_add_f32_e32 v65, v89, v65
	v_add_f32_e32 v48, v80, v48
	v_add_f32_e32 v49, v81, v49
	v_add_f32_e32 v34, v34, v54
	v_add_f32_e32 v35, v35, v55
	v_add_f32_e32 v36, v36, v60
	v_add_f32_e32 v37, v37, v61
	v_add_f32_e32 v38, v38, v62
	v_add_f32_e32 v39, v39, v63
	s_waitcnt lgkmcnt(2)
	v_add_f32_e32 v40, v40, v68
	v_add_f32_e32 v41, v41, v69
	v_add_f32_e32 v42, v42, v70
	v_add_f32_e32 v43, v43, v71
	s_waitcnt lgkmcnt(0)
; __device__ __forceinline__ void cmask(f32x16&p0,f32x16&p1,int jb,int qrel,int hi){
;   const float NEG=-INFINITY; int kb=64*jb+4*hi;
;   #pragma unroll
;   for(int r=0;r<16;++r){int kv=kb+(r&3)+8*(r>>2); if(kv>qrel)p0[r]=NEG; if(kv+32>qrel)p1[r]=NEG;}
; }
	v_add_f32_e32 v44, v44, v76
	v_add_f32_e32 v45, v45, v77
	v_add_f32_e32 v46, v46, v78
	v_add_f32_e32 v47, v47, v79
	v_add_f32_e32 v32, v32, v52
	v_add_f32_e32 v33, v33, v53
	v_add_f32_e32 v66, v90, v66
	v_add_f32_e32 v67, v91, v67
	v_add_f32_e32 v72, v92, v72
	v_add_f32_e32 v73, v93, v73
	v_add_f32_e32 v74, v94, v74
	v_add_f32_e32 v75, v95, v75
	v_or_b32_e32 v53, 0xe0, v225
	v_or_b32_e32 v52, 0xc0, v225
	v_cmp_le_i32_e32 vcc, v53, v226
	v_or_b32_e32 v53, 0xe8, v225
	v_or_b32_e32 v54, 0xe9, v225
	v_cndmask_b32_e32 v32, v216, v32, vcc
	v_cmp_lt_i32_e32 vcc, v52, v226
	v_or_b32_e32 v55, 0xea, v225
	v_or_b32_e32 v60, 0xf3, v225
	v_cndmask_b32_e32 v49, v216, v49, vcc
	v_cmp_le_i32_e32 vcc, v52, v226
	v_or_b32_e32 v52, 0xe1, v225
	v_or_b32_e32 v61, 0xf8, v225
	v_cndmask_b32_e32 v48, v216, v48, vcc
	v_cmp_le_i32_e32 vcc, v52, v226
	v_or_b32_e32 v52, 0xc2, v225
	v_or_b32_e32 v62, 0xf9, v225
	v_cndmask_b32_e32 v33, v216, v33, vcc
	v_cmp_le_i32_e32 vcc, v52, v226
	v_or_b32_e32 v52, 0xe2, v225
	v_or_b32_e32 v63, 0xfa, v225
	v_cndmask_b32_e32 v50, v216, v50, vcc
	v_cmp_le_i32_e32 vcc, v52, v226
	v_or_b32_e32 v52, 0xc3, v225
	v_add_f32_e32 v80, v231, v116
	v_cndmask_b32_e32 v34, v216, v34, vcc
	v_cmp_le_i32_e32 vcc, v52, v226
	v_or_b32_e32 v52, 0xe3, v225
	s_nop 0
	v_cndmask_b32_e32 v51, v216, v51, vcc
	v_cmp_le_i32_e32 vcc, v52, v226
	v_or_b32_e32 v52, 0xc8, v225
	s_nop 0
	v_cndmask_b32_e32 v35, v216, v35, vcc
	v_cmp_le_i32_e32 vcc, v52, v226
	s_nop 1
	v_cndmask_b32_e32 v52, v216, v56, vcc
	v_cmp_le_i32_e32 vcc, v53, v226
	v_or_b32_e32 v53, 0xc9, v225
	v_or_b32_e32 v56, 0xeb, v225
	v_cndmask_b32_e32 v36, v216, v36, vcc
	v_cmp_le_i32_e32 vcc, v53, v226
	s_nop 1
	v_cndmask_b32_e32 v53, v216, v57, vcc
	v_cmp_le_i32_e32 vcc, v54, v226
	v_or_b32_e32 v54, 0xca, v225
	v_or_b32_e32 v57, 0xf0, v225
	v_cndmask_b32_e32 v37, v216, v37, vcc
	v_cmp_le_i32_e32 vcc, v54, v226
	s_nop 1
	v_cndmask_b32_e32 v54, v216, v58, vcc
	v_cmp_le_i32_e32 vcc, v55, v226
	v_or_b32_e32 v55, 0xcb, v225
	v_or_b32_e32 v58, 0xf1, v225
	v_cndmask_b32_e32 v38, v216, v38, vcc
	v_cmp_le_i32_e32 vcc, v55, v226
	s_nop 1
	v_cndmask_b32_e32 v55, v216, v59, vcc
	v_cmp_le_i32_e32 vcc, v56, v226
	v_or_b32_e32 v56, 0xd0, v225
	v_or_b32_e32 v59, 0xf2, v225
	v_cndmask_b32_e32 v39, v216, v39, vcc
	v_cmp_le_i32_e32 vcc, v56, v226
	s_nop 1
	v_cndmask_b32_e32 v56, v216, v64, vcc
	v_cmp_le_i32_e32 vcc, v57, v226
	v_or_b32_e32 v57, 0xd1, v225
	v_or_b32_e32 v64, 0xfb, v225
	v_cndmask_b32_e32 v40, v216, v40, vcc
	v_cmp_le_i32_e32 vcc, v57, v226
	s_nop 1
	v_cndmask_b32_e32 v57, v216, v65, vcc
	v_cmp_le_i32_e32 vcc, v58, v226
	v_or_b32_e32 v58, 0xd2, v225
	v_max3_f32 v65, v50, v51, v33
	v_cndmask_b32_e32 v41, v216, v41, vcc
	v_cmp_le_i32_e32 vcc, v58, v226
	v_max3_f32 v65, v65, v54, v55
	v_max3_f32 v65, v65, v38, v39
	v_cndmask_b32_e32 v58, v216, v66, vcc
	v_cmp_le_i32_e32 vcc, v59, v226
	v_or_b32_e32 v59, 0xd3, v225
	s_nop 0
	v_cndmask_b32_e32 v42, v216, v42, vcc
	v_cmp_le_i32_e32 vcc, v59, v226
	s_nop 1
	v_cndmask_b32_e32 v59, v216, v67, vcc
	v_cmp_le_i32_e32 vcc, v60, v226
	v_or_b32_e32 v60, 0xd8, v225
	v_max3_f32 v65, v65, v58, v59
	v_cndmask_b32_e32 v43, v216, v43, vcc
	v_cmp_le_i32_e32 vcc, v60, v226
	v_max3_f32 v65, v65, v42, v43
	s_nop 0
	v_cndmask_b32_e32 v60, v216, v72, vcc
	v_cmp_le_i32_e32 vcc, v61, v226
	v_or_b32_e32 v61, 0xd9, v225
	s_nop 0
	v_cndmask_b32_e32 v44, v216, v44, vcc
	v_cmp_le_i32_e32 vcc, v61, v226
	s_nop 1
	v_cndmask_b32_e32 v61, v216, v73, vcc
	v_cmp_le_i32_e32 vcc, v62, v226
	v_or_b32_e32 v62, 0xda, v225
	s_nop 0
	v_cndmask_b32_e32 v45, v216, v45, vcc
	v_cmp_le_i32_e32 vcc, v62, v226
	s_nop 1
	v_cndmask_b32_e32 v62, v216, v74, vcc
	v_cmp_le_i32_e32 vcc, v63, v226
	v_or_b32_e32 v63, 0xdb, v225
	s_nop 0
	v_cndmask_b32_e32 v46, v216, v46, vcc
	v_cmp_le_i32_e32 vcc, v63, v226
	s_nop 1
	v_cndmask_b32_e32 v63, v216, v75, vcc
	v_cmp_le_i32_e32 vcc, v64, v226
	v_max_f32_e32 v64, v48, v49
	v_max3_f32 v64, v64, v32, v34
	v_max3_f32 v64, v64, v35, v52
	v_max3_f32 v64, v64, v53, v36
	v_max3_f32 v64, v64, v37, v56
	v_max3_f32 v64, v64, v57, v40
	v_cndmask_b32_e32 v47, v216, v47, vcc
	v_max3_f32 v64, v64, v41, v60
	v_max3_f32 v65, v65, v62, v63
	v_max3_f32 v64, v64, v61, v44
	v_max3_f32 v65, v65, v46, v47
	v_max3_f32 v64, v64, v45, v65
	v_mov_b32_e32 v65, v64
	s_nop 1
	v_permlane32_swap_b32_e32 v64, v65
	v_max_f32_e32 v64, v64, v65
	v_cmp_lt_f32_e32 vcc, s61, v64
	s_cmp_lg_u64 vcc, 0
	s_cselect_b64 s[8:9], -1, 0
	s_cbranch_vccnz .LBB0_858

.LBB0_814:
	v_max_f32_e32 v80, v65, v65
	v_max_f32_e32 v81, v64, v64
	v_max_f32_e32 v80, v81, v80
	v_max3_f32 v81, v66, v67, v49
	v_max3_f32 v80, v80, v48, v50
	v_max3_f32 v80, v80, v51, v68
	v_max3_f32 v81, v81, v70, v71
	v_max3_f32 v80, v80, v69, v52
	v_max3_f32 v81, v81, v54, v55
	v_max3_f32 v80, v80, v53, v72
	v_max3_f32 v81, v81, v74, v75
	v_max3_f32 v80, v80, v73, v56
	v_max3_f32 v81, v81, v58, v59
	v_max3_f32 v80, v80, v57, v76
	v_max3_f32 v81, v81, v78, v79
	v_max3_f32 v80, v80, v77, v60
	v_max3_f32 v81, v81, v62, v63
	v_max3_f32 v80, v80, v61, v81
	v_mov_b32_e32 v81, v80
	s_nop 1
	v_permlane32_swap_b32_e32 v80, v81
	v_max_f32_e32 v80, v80, v81
	v_cmp_lt_f32_e32 vcc, s61, v80
	s_cmp_lg_u64 vcc, 0
	v_add_f32_e32 v231, v231, v148
	s_cselect_b64 s[10:11], -1, 0
	s_cbranch_vccnz .LBB0_852

.LBB0_825:
	v_max_f32_e32 v80, v65, v65
	v_max_f32_e32 v81, v64, v64
	v_max_f32_e32 v80, v81, v80
	v_max3_f32 v81, v66, v67, v49
	v_max3_f32 v80, v80, v48, v50
	v_max3_f32 v80, v80, v51, v68
	v_max3_f32 v81, v81, v70, v71
	v_max3_f32 v80, v80, v69, v52
	v_max3_f32 v81, v81, v54, v55
	v_max3_f32 v80, v80, v53, v72
	v_max3_f32 v81, v81, v74, v75
	v_max3_f32 v80, v80, v73, v56
	v_max3_f32 v81, v81, v58, v59
	v_max3_f32 v80, v80, v57, v76
	v_max3_f32 v81, v81, v78, v79
	v_max3_f32 v80, v80, v77, v60
	v_max3_f32 v81, v81, v62, v63
	v_max3_f32 v80, v80, v61, v81
	v_mov_b32_e32 v81, v80
	s_nop 1
	v_permlane32_swap_b32_e32 v80, v81
	v_max_f32_e32 v80, v80, v81
	v_cmp_lt_f32_e32 vcc, s61, v80
	s_cmp_lg_u64 vcc, 0
	v_add_f32_e32 v231, v231, v234
	s_cselect_b64 s[44:45], -1, 0
	s_cbranch_vccnz .LBB0_855

; #define LAS __attribute__((address_space(3)))
; #define MFMA32(a, b, c) __builtin_amdgcn_mfma_f32_32x32x16_bf16((a), (b), (c), 0, 0, 0)
; __device__ __forceinline__ void qk_tile(f32x16& p0, f32x16& p1, LAS const unsigned char* Kt, const bf16x8 (&qf)[4], int lane) {
;     LAS const unsigned char* kp = Kt + (lane & 31) * KVP + 16 * (lane >> 5);
;     f32x16 z = {}; p0 = z; p1 = z;
; #pragma unroll
;     for (int s = 0; s < 4; ++s) { const bf16x8 a0 = *(LAS const bf16x8*)(kp + 32 * s), a1 = *(LAS const bf16x8*)(kp + 32 * KVP + 32 * s);
;         p0 = MFMA32(a0, qf[s], p0); p1 = MFMA32(a1, qf[s], p1); }
; }
; __device__ __forceinline__ void nsa_unit(int b, int g, int tq, const Args& a, LAS unsigned char* lds, int tid, int wave, int lane, int& nxt) {
;     ...
;     tile_st(cmpb, ck0, tid); tile_st_v(cmpb + 2 * KVT, cv0, tid); tile_st(cmpb + KVT, ck1, tid); tile_st_v(cmpb + 3 * KVT, cv1, tid);
;     if (tid == 0) uni[0] = 0u;
;     __syncthreads();
;     f32x16 acc0, acc1;
;     {
.LBB0_895:
	s_or_b64 exec, exec, s[8:9]
	v_mul_lo_u32 v19, v80, s80
	v_add3_u32 v0, 0, v19, v0
	s_waitcnt vmcnt(14)
	s_waitcnt vmcnt(13)
	s_waitcnt vmcnt(12)
	s_waitcnt vmcnt(11)
	s_waitcnt vmcnt(8)
	s_waitcnt vmcnt(6)
	ds_write_b128 v0, v[6:9] offset:49152
	v_lshlrev_b32_e32 v7, 2, v86
	v_and_b32_e32 v7, 64, v7
	s_movk_i32 s0, 0x70
	v_and_b32_e32 v6, 0xffffff80, v18
	v_bitop3_b32 v7, v18, v7, s0 bitop3:0x6c
	v_add3_u32 v8, s81, v6, v7
	s_waitcnt vmcnt(4)
	ds_write_b128 v8, v[2:5]
	s_waitcnt vmcnt(2)
	ds_write_b128 v0, v[10:13] offset:58368
	v_add3_u32 v0, s82, v6, v7
	s_waitcnt vmcnt(0)
	ds_write_b128 v0, v[14:17]
	s_and_saveexec_b64 s[4:5], vcc
	v_mov_b32_e32 v0, s83
	ds_write_b32 v0, v1
	s_or_b64 exec, exec, s[4:5]
	v_lshrrev_b32_e32 v2, 1, v86
	v_mad_u32_u24 v0, v84, s80, 0
	v_and_b32_e32 v2, 16, v2
	v_add_u32_e32 v89, v0, v2
	s_waitcnt lgkmcnt(0)
	s_barrier
	ds_read_b128 v[2:5], v89 offset:49152
	ds_read_b128 v[36:39], v89 offset:49184
	ds_read_b128 v[18:21], v89 offset:53760
	ds_read_b128 v[40:43], v89 offset:53792
	s_waitcnt lgkmcnt(3)
	v_mfma_f32_32x32x16_bf16 v[2:17], v[2:5], v[144:147], 0
	ds_read_b128 v[44:47], v89 offset:49216
	ds_read_b128 v[48:51], v89 offset:49248
	ds_read_b128 v[52:55], v89 offset:53824
	ds_read_b128 v[56:59], v89 offset:53856
	v_lshlrev_b32_e32 v90, 6, v83
	s_mul_i32 s0, s6, 0x500
	v_subrev_u32_e32 v0, 31, v178
	v_or_b32_e32 v91, 16, v90
	v_or_b32_e32 v92, 32, v90
	v_or_b32_e32 v93, 48, v90
	s_waitcnt lgkmcnt(5)
	v_mfma_f32_32x32x16_bf16 v[18:33], v[18:21], v[144:147], 0
	s_add_i32 s96, s0, 0
	s_add_i32 s96, s96, 0x1d600
	v_or_b32_e32 v94, 0x80, v90
	v_or_b32_e32 v95, 0x90, v90
	v_or_b32_e32 v96, 0xa0, v90
	v_or_b32_e32 v97, 0xb0, v90
	v_or_b32_e32 v98, 0x100, v90
	s_waitcnt lgkmcnt(4)
	v_mfma_f32_32x32x16_bf16 v[18:33], v[40:43], v[148:151], v[18:33]
	v_sub_u32_e32 v40, v0, v92
	v_sub_u32_e32 v42, v0, v93
	v_med3_i32 v41, v40, -1, v170
	v_med3_i32 v40, v40, s86, v171
	v_med3_i32 v43, v42, -1, v170
	v_med3_i32 v42, v42, s86, v171
	v_lshl_add_u32 v40, v40, 2, s96
	v_mfma_f32_32x32x16_bf16 v[2:17], v[36:39], v[148:151], v[2:17]
	v_sub_u32_e32 v36, v0, v90
	v_sub_u32_e32 v38, v0, v91
	v_med3_i32 v37, v36, -1, v170
	v_med3_i32 v36, v36, s86, v171
	v_med3_i32 v39, v38, -1, v170
	v_med3_i32 v38, v38, s86, v171
	v_lshl_add_u32 v36, v36, 2, s96
	s_waitcnt lgkmcnt(1)
	v_mfma_f32_32x32x16_bf16 v[18:33], v[52:55], v[152:155], v[18:33]
	v_lshl_add_u32 v38, v38, 2, s96
	v_lshl_add_u32 v42, v42, 2, s96
	v_lshl_add_u32 v37, v37, 2, s96
	v_add_u32_e32 v36, 0xfffff900, v36
	v_lshl_add_u32 v39, v39, 2, s96
	v_add_u32_e32 v38, 0xfffff900, v38
	v_lshl_add_u32 v41, v41, 2, s96
	v_mfma_f32_32x32x16_bf16 v[2:17], v[44:47], v[152:155], v[2:17]
	v_add_u32_e32 v40, 0xfffff900, v40
	v_lshl_add_u32 v43, v43, 2, s96
	v_add_u32_e32 v42, 0xfffff900, v42
	ds_read_b32 v37, v37 offset:256
	ds_read_b32 v36, v36
	ds_read_b32 v39, v39 offset:256
	ds_read_b32 v38, v38
	ds_read_b32 v41, v41 offset:256
	ds_read_b32 v40, v40
	ds_read_b32 v43, v43 offset:256
	ds_read_b32 v42, v42
	v_or_b32_e32 v99, 0x110, v90
	v_or_b32_e32 v100, 0x120, v90
	v_or_b32_e32 v101, 0x130, v90
	s_waitcnt lgkmcnt(8)
	v_mfma_f32_32x32x16_bf16 v[18:33], v[56:59], v[156:159], v[18:33]
	v_or_b32_e32 v102, 0x180, v90
	v_or_b32_e32 v103, 0x190, v90
	v_or_b32_e32 v104, 0x1a0, v90
	v_or_b32_e32 v105, 0x1b0, v90
	v_cmp_gt_u32_e64 s[4:5], 32, v174
	v_or_b32_e32 v87, s78, v85
	v_lshlrev_b32_e32 v179, 2, v83
	v_mfma_f32_32x32x16_bf16 v[2:17], v[48:51], v[156:159], v[2:17]
	s_waitcnt lgkmcnt(6)
	s_nop 2
	v_add_f32_e32 v18, v18, v36
	s_waitcnt lgkmcnt(4)
	v_add_f32_e32 v19, v19, v38
	s_waitcnt lgkmcnt(2)
	v_add_f32_e32 v20, v20, v40
	s_waitcnt lgkmcnt(0)
	v_add_f32_e32 v21, v21, v42
	v_sub_u32_e32 v36, v0, v94
	v_sub_u32_e32 v38, v0, v95
	v_sub_u32_e32 v40, v0, v96
	v_sub_u32_e32 v42, v0, v97
	v_add_f32_e32 v2, v2, v37
	v_add_f32_e32 v3, v3, v39
	v_add_f32_e32 v4, v4, v41
	v_add_f32_e32 v5, v5, v43
	v_med3_i32 v37, v36, -1, v170
	v_med3_i32 v36, v36, s86, v171
	v_med3_i32 v39, v38, -1, v170
	v_med3_i32 v38, v38, s86, v171
	v_med3_i32 v41, v40, -1, v170
	v_med3_i32 v40, v40, s86, v171
	v_med3_i32 v43, v42, -1, v170
	v_med3_i32 v42, v42, s86, v171
	v_lshl_add_u32 v36, v36, 2, s96
	v_lshl_add_u32 v38, v38, 2, s96
	v_lshl_add_u32 v40, v40, 2, s96
	v_lshl_add_u32 v42, v42, 2, s96
	v_lshl_add_u32 v37, v37, 2, s96
	v_add_u32_e32 v36, 0xfffff900, v36
	v_lshl_add_u32 v39, v39, 2, s96
	v_add_u32_e32 v38, 0xfffff900, v38
	v_lshl_add_u32 v41, v41, 2, s96
	v_add_u32_e32 v40, 0xfffff900, v40
	v_lshl_add_u32 v43, v43, 2, s96
	v_add_u32_e32 v42, 0xfffff900, v42
	ds_read_b32 v37, v37 offset:256
	ds_read_b32 v36, v36
	ds_read_b32 v39, v39 offset:256
	ds_read_b32 v38, v38
	ds_read_b32 v41, v41 offset:256
	ds_read_b32 v40, v40
	ds_read_b32 v43, v43 offset:256
	ds_read_b32 v42, v42
	s_waitcnt lgkmcnt(6)
	v_add_f32_e32 v22, v22, v36
	s_waitcnt lgkmcnt(4)
	v_add_f32_e32 v23, v23, v38
	s_waitcnt lgkmcnt(3)
	v_add_f32_e32 v36, v8, v41
	s_waitcnt lgkmcnt(2)
	v_add_f32_e32 v24, v24, v40
	s_waitcnt lgkmcnt(0)
	v_add_f32_e32 v25, v25, v42
	v_sub_u32_e32 v8, v0, v98
	v_sub_u32_e32 v38, v0, v99
	v_sub_u32_e32 v40, v0, v100
	v_sub_u32_e32 v42, v0, v101
	v_add_f32_e32 v6, v6, v37
	v_add_f32_e32 v7, v7, v39
	v_add_f32_e32 v9, v9, v43
	v_med3_i32 v37, v8, -1, v170
	v_med3_i32 v8, v8, s86, v171
	v_med3_i32 v39, v38, -1, v170
	v_med3_i32 v38, v38, s86, v171
	v_med3_i32 v41, v40, -1, v170
	v_med3_i32 v40, v40, s86, v171
	v_med3_i32 v43, v42, -1, v170
	v_med3_i32 v42, v42, s86, v171
	v_lshl_add_u32 v8, v8, 2, s96
	v_lshl_add_u32 v38, v38, 2, s96
	v_lshl_add_u32 v40, v40, 2, s96
	v_lshl_add_u32 v42, v42, 2, s96
	v_lshl_add_u32 v37, v37, 2, s96
	v_add_u32_e32 v8, 0xfffff900, v8
	v_lshl_add_u32 v39, v39, 2, s96
	v_add_u32_e32 v38, 0xfffff900, v38
	v_lshl_add_u32 v41, v41, 2, s96
	v_add_u32_e32 v40, 0xfffff900, v40
	v_lshl_add_u32 v43, v43, 2, s96
	v_add_u32_e32 v42, 0xfffff900, v42
	ds_read_b32 v37, v37 offset:256
	ds_read_b32 v8, v8
	ds_read_b32 v39, v39 offset:256
	ds_read_b32 v38, v38
	ds_read_b32 v41, v41 offset:256
	ds_read_b32 v40, v40
	ds_read_b32 v43, v43 offset:256
	ds_read_b32 v42, v42
	s_waitcnt lgkmcnt(6)
; #define LAS __attribute__((address_space(3)))
; __device__ __forceinline__ void nsa_unit(int b, int g, int tq, const Args& a, LAS unsigned char* lds, int tid, int wave, int lane, int& nxt) {
;     ...
;         f32x16 p0, p1; float mx = NEG, sum = 0.f;
;         f32x16 z = {}; acc0 = z; acc1 = z;
;         LAS float* ip = imp + (hr * 64 + tl) * 33 + h; float carry = 0.f;
	v_add_f32_e32 v26, v26, v8
	s_waitcnt lgkmcnt(4)
	v_add_f32_e32 v27, v27, v38
	s_waitcnt lgkmcnt(2)
	v_add_f32_e32 v28, v28, v40
	s_waitcnt lgkmcnt(1)
	v_add_f32_e32 v38, v13, v43
	v_sub_u32_e32 v8, v0, v102
	v_sub_u32_e32 v13, v0, v103
	v_sub_u32_e32 v40, v0, v104
	v_sub_u32_e32 v0, v0, v105
	v_add_f32_e32 v10, v10, v37
	v_add_f32_e32 v11, v11, v39
	v_add_f32_e32 v37, v12, v41
	s_waitcnt lgkmcnt(0)
	v_add_f32_e32 v29, v29, v42
	v_med3_i32 v12, v8, -1, v170
	v_med3_i32 v8, v8, s86, v171
	v_med3_i32 v39, v13, -1, v170
	v_med3_i32 v13, v13, s86, v171
	v_med3_i32 v41, v40, -1, v170
	v_med3_i32 v40, v40, s86, v171
	v_med3_i32 v42, v0, -1, v170
	v_med3_i32 v0, v0, s86, v171
	v_lshl_add_u32 v8, v8, 2, s96
	v_lshl_add_u32 v13, v13, 2, s96
	v_lshl_add_u32 v40, v40, 2, s96
	v_lshl_add_u32 v0, v0, 2, s96
	v_lshl_add_u32 v12, v12, 2, s96
	v_add_u32_e32 v8, 0xfffff900, v8
	v_lshl_add_u32 v39, v39, 2, s96
	v_add_u32_e32 v13, 0xfffff900, v13
	v_lshl_add_u32 v41, v41, 2, s96
	v_add_u32_e32 v40, 0xfffff900, v40
	v_lshl_add_u32 v42, v42, 2, s96
	v_add_u32_e32 v0, 0xfffff900, v0
	ds_read_b32 v12, v12 offset:256
	ds_read_b32 v8, v8
	ds_read_b32 v39, v39 offset:256
	ds_read_b32 v13, v13
	ds_read_b32 v41, v41 offset:256
	ds_read_b32 v40, v40
	ds_read_b32 v42, v42 offset:256
	ds_read_b32 v0, v0
	s_waitcnt lgkmcnt(5)
	v_add_f32_e32 v15, v15, v39
	v_add_f32_e32 v43, v14, v12
	s_waitcnt lgkmcnt(2)
	v_add_f32_e32 v39, v32, v40
	v_add_f32_e32 v30, v30, v8
	s_waitcnt lgkmcnt(0)
	v_add_f32_e32 v40, v33, v0
	v_max_f32_e32 v0, v3, v19
	v_max3_f32 v0, v2, v18, v0
	v_max_f32_e32 v8, v4, v20
	v_max_f32_e32 v12, v5, v21
	v_max3_f32 v0, v0, v8, v12
	v_max_f32_e32 v8, v6, v22
	v_max_f32_e32 v12, v7, v23
	v_max3_f32 v0, v0, v8, v12
	v_max_f32_e32 v8, v36, v24
	v_max_f32_e32 v12, v9, v25
	v_max3_f32 v0, v0, v8, v12
	v_max_f32_e32 v8, v10, v26
	v_max_f32_e32 v12, v11, v27
	v_add_f32_e32 v31, v31, v13
	v_max3_f32 v0, v0, v8, v12
	v_max_f32_e32 v8, v37, v28
	v_max_f32_e32 v12, v38, v29
	v_add_f32_e32 v16, v16, v41
	v_add_f32_e32 v17, v17, v42
	v_max3_f32 v0, v0, v8, v12
	v_max_f32_e32 v8, v43, v30
	v_max_f32_e32 v12, v15, v31
	v_max3_f32 v0, v0, v8, v12
	v_max_f32_e32 v8, v16, v39
	v_max_f32_e32 v12, v17, v40
	v_max3_f32 v0, v0, v8, v12
	v_mov_b32_e32 v8, v0
	s_nop 1
	v_permlane32_swap_b32_e32 v0, v8
	v_max3_f32 v81, v0, v8, s55
	v_sub_f32_e32 v0, v2, v81
	v_sub_f32_e32 v2, v4, v81
	v_sub_f32_e32 v4, v10, v81
	v_exp_f32_e32 v41, v0
	v_sub_f32_e32 v0, v18, v81
	v_exp_f32_e32 v42, v2
	v_sub_f32_e32 v2, v20, v81
	v_exp_f32_e32 v59, v4
	v_sub_f32_e32 v4, v26, v81
	v_exp_f32_e32 v51, v0
	v_sub_f32_e32 v0, v3, v81
	v_exp_f32_e32 v53, v2
	v_sub_f32_e32 v2, v5, v81
	v_sub_f32_e32 v3, v6, v81
	v_exp_f32_e32 v76, v4
	v_sub_f32_e32 v4, v25, v81
	v_sub_f32_e32 v6, v37, v81
	v_exp_f32_e32 v60, v2
	v_sub_f32_e32 v2, v21, v81
	v_exp_f32_e32 v14, v4
	v_sub_f32_e32 v4, v11, v81
	v_exp_f32_e32 v11, v6
	v_sub_f32_e32 v6, v28, v81
	v_exp_f32_e32 v8, v2
	v_sub_f32_e32 v2, v7, v81
	v_exp_f32_e32 v77, v6
	v_sub_f32_e32 v6, v38, v81
	v_exp_f32_e32 v56, v2
	v_sub_f32_e32 v2, v23, v81
	v_exp_f32_e32 v54, v6
	v_sub_f32_e32 v6, v29, v81
	v_exp_f32_e32 v58, v2
	v_sub_f32_e32 v2, v9, v81
	v_exp_f32_e32 v50, v6
	v_sub_f32_e32 v6, v43, v81
	v_sub_f32_e32 v9, v31, v81
	v_exp_f32_e32 v32, v0
	v_exp_f32_e32 v72, v6
	v_sub_f32_e32 v6, v30, v81
	v_exp_f32_e32 v10, v9
	v_sub_f32_e32 v9, v16, v81
	v_exp_f32_e32 v78, v6
	v_sub_f32_e32 v6, v15, v81
	v_exp_f32_e32 v15, v9
	v_sub_f32_e32 v9, v39, v81
	v_exp_f32_e32 v79, v9
	v_sub_f32_e32 v9, v17, v81
	v_exp_f32_e32 v5, v3
	v_sub_f32_e32 v3, v22, v81
	v_exp_f32_e32 v48, v9
	v_sub_f32_e32 v9, v40, v81
	v_exp_f32_e32 v74, v3
	v_sub_f32_e32 v3, v36, v81
	v_exp_f32_e32 v52, v9
	v_add_f32_e32 v9, v41, v32
	v_add_f32_e32 v16, v42, v60
	v_exp_f32_e32 v7, v3
	v_exp_f32_e32 v2, v2
	v_add_f32_e32 v9, v9, v16
	v_mov_b32_e32 v16, v60
	v_mov_b32_e32 v17, v60
	s_nop 1
	v_permlane32_swap_b32_e32 v16, v17
	v_cndmask_b32_e64 v16, v16, v17, s[4:5]
	v_mul_lo_u32 v18, v87, s85
	v_cndmask_b32_e64 v17, v16, 0, s[4:5]
	v_add3_u32 v88, s84, v18, v179
	v_add_f32_e32 v9, v17, v9
	v_add_f32_e32 v17, v5, v56
	v_add_f32_e32 v18, v7, v2
	v_sub_f32_e32 v0, v19, v81
	v_add_f32_e32 v17, v17, v18
	v_mov_b32_e32 v18, v2
	v_mov_b32_e32 v19, v2
	v_exp_f32_e32 v12, v4
	s_nop 0
	v_permlane32_swap_b32_e32 v18, v19
	v_cndmask_b32_e64 v18, v18, v19, s[4:5]
	v_cndmask_b32_e64 v16, v18, v16, s[4:5]
	v_add_f32_e32 v16, v16, v17
	ds_write2_b32 v88, v9, v16 offset1:2
	v_add_f32_e32 v9, v59, v12
	v_add_f32_e32 v16, v11, v54
	v_exp_f32_e32 v6, v6
	v_add_f32_e32 v9, v9, v16
	v_mov_b32_e32 v16, v54
	v_mov_b32_e32 v17, v54
	s_nop 1
	v_permlane32_swap_b32_e32 v16, v17
	v_cndmask_b32_e64 v16, v16, v17, s[4:5]
	v_cndmask_b32_e64 v17, v16, v18, s[4:5]
	v_add_f32_e32 v9, v9, v17
	v_add_f32_e32 v17, v72, v6
	v_add_f32_e32 v18, v15, v48
	v_add_f32_e32 v17, v17, v18
	v_mov_b32_e32 v18, v48
	v_mov_b32_e32 v19, v48
	v_exp_f32_e32 v0, v0
	s_nop 0
	v_permlane32_swap_b32_e32 v18, v19
	v_cndmask_b32_e64 v18, v18, v19, s[4:5]
	v_cndmask_b32_e64 v16, v18, v16, s[4:5]
	v_add_f32_e32 v16, v17, v16
	v_sub_f32_e32 v3, v24, v81
	ds_write2_b32 v88, v9, v16 offset0:4 offset1:6
	v_add_f32_e32 v9, v51, v0
	v_add_f32_e32 v16, v53, v8
	v_exp_f32_e32 v75, v3
	v_add_f32_e32 v9, v9, v16
	v_mov_b32_e32 v16, v8
	v_mov_b32_e32 v17, v8
	s_nop 1
	v_permlane32_swap_b32_e32 v16, v17
	v_cndmask_b32_e64 v16, v16, v17, s[4:5]
	v_cndmask_b32_e64 v17, v16, v18, s[4:5]
	v_add_f32_e32 v9, v9, v17
	v_add_f32_e32 v17, v74, v58
	v_add_f32_e32 v18, v75, v14
	v_sub_f32_e32 v4, v27, v81
	v_add_f32_e32 v17, v17, v18
	v_mov_b32_e32 v18, v14
	v_mov_b32_e32 v19, v14
; __device__ __forceinline__ s16x4 vtr(lds_cptr p){ return __builtin_bit_cast(s16x4,__builtin_amdgcn_ds_read_tr16_b64_v4i16((__attribute__((address_space(3))) v4i16_t*)p)); }
; #define LAS __attribute__((address_space(3)))
; #define MFMA32(a, b, c) __builtin_amdgcn_mfma_f32_32x32x16_bf16((a), (b), (c), 0, 0, 0)
; __device__ __forceinline__ s16x4 vtr(LAS const unsigned char* p) { return __builtin_bit_cast(s16x4, __builtin_amdgcn_ds_read_tr16_b64_v4i16((LAS v4i16_t*)p)); }
; __device__ __forceinline__ void pv_tile(f32x16& o0, f32x16& o1, LAS const unsigned char* Vt, const bf16x8 (&pf)[4], int lane) {
;     const int q = (lane & 15) >> 2, swz = ((q >> 1) & 1) * 64;
;     LAS const unsigned char* vp0 = Vt + (4 * (lane >> 5) + q) * 128 + (((16 * ((lane >> 4) & 1) + 4 * (lane & 3)) * 2) ^ swz);
;     LAS const unsigned char* vp1 = Vt + (4 * (lane >> 5) + q) * 128 + (((16 * ((lane >> 4) & 1) + 4 * (lane & 3)) * 2 + 64) ^ swz);
; #pragma unroll
;     for (int s = 0; s < 4; ++s) {
;         const s16x4 l0 = vtr(vp0 + (16 * s) * 128), h0 = vtr(vp0 + (16 * s + 8) * 128), l1 = vtr(vp1 + (16 * s) * 128), h1 = vtr(vp1 + (16 * s + 8) * 128);
;         const bf16x8 v0 = {l0[0], l0[1], l0[2], l0[3], h0[0], h0[1], h0[2], h0[3]}, v1 = {l1[0], l1[1], l1[2], l1[3], h1[0], h1[1], h1[2], h1[3]};
;         o0 = MFMA32(v0, pf[s], o0); o1 = MFMA32(v1, pf[s], o1); }
; }
; __device__ __forceinline__ void nsa_unit(int b, int g, int tq, const Args& a, LAS unsigned char* lds, int tid, int wave, int lane, int& nxt) {
;     ...
;         CMP_TILE(0);
;         const float m_t0 = mx;
;         if (nct > 1) CMP_TILE(1);
	v_exp_f32_e32 v4, v4
	s_nop 0
	v_permlane32_swap_b32_e32 v18, v19
	v_cndmask_b32_e64 v18, v18, v19, s[4:5]
	v_cndmask_b32_e64 v16, v18, v16, s[4:5]
	v_add_f32_e32 v16, v17, v16
	ds_write2_b32 v88, v9, v16 offset0:8 offset1:10
	v_add_f32_e32 v9, v76, v4
	v_add_f32_e32 v16, v77, v50
	v_add_f32_e32 v9, v9, v16
	v_mov_b32_e32 v16, v50
	v_mov_b32_e32 v17, v50
	s_nop 1
	v_permlane32_swap_b32_e32 v16, v17
	v_cndmask_b32_e64 v16, v16, v17, s[4:5]
	v_cndmask_b32_e64 v17, v16, v18, s[4:5]
	v_add_f32_e32 v9, v9, v17
	v_add_f32_e32 v17, v78, v10
	v_add_f32_e32 v18, v79, v52
	v_add_f32_e32 v17, v17, v18
	v_mov_b32_e32 v18, v52
	v_mov_b32_e32 v19, v52
	s_nop 1
	v_permlane32_swap_b32_e32 v18, v19
	v_cndmask_b32_e64 v106, v18, v19, s[4:5]
	v_cndmask_b32_e64 v16, v106, v16, s[4:5]
	v_add_f32_e32 v16, v17, v16
	ds_write2_b32 v88, v9, v16 offset0:12 offset1:14
	v_bfe_u32 v9, v174, 2, 2
	v_and_or_b32 v9, v34, 4, v9
	v_and_b32_e32 v16, 16, v86
	v_lshlrev_b32_e32 v17, 2, v174
	v_lshlrev_b32_e32 v20, 5, v35
	v_lshlrev_b32_e32 v128, 7, v9
	v_and_or_b32 v16, v17, 12, v16
	v_and_b32_e32 v180, 64, v20
	v_add_u32_e32 v9, s81, v128
	v_lshlrev_b32_e32 v181, 1, v16
	v_add3_u32 v107, v9, v181, v180
	ds_read_b64_tr_b16 v[16:17], v107
	ds_read_b64_tr_b16 v[18:19], v107 offset:1024
	v_bitop3_b32 v182, v181, v20, 64 bitop3:0x72
	v_add_u32_e32 v108, v9, v182
	v_add_f32_e32 v33, v41, v51
	v_add_f32_e32 v61, v42, v53
	v_cvt_pk_bf16_f32 v36, v41, v32
	v_cvt_pk_bf16_f32 v37, v42, v60
	ds_read_b64_tr_b16 v[40:41], v108
	ds_read_b64_tr_b16 v[42:43], v108 offset:1024
	ds_read_b64_tr_b16 v[62:63], v107 offset:2048
	ds_read_b64_tr_b16 v[64:65], v107 offset:3072
	v_cvt_pk_bf16_f32 v38, v5, v56
	v_cvt_pk_bf16_f32 v39, v7, v2
	v_add_f32_e32 v32, v32, v0
	v_add_f32_e32 v33, v33, v1
	ds_read_b64_tr_b16 v[66:67], v108 offset:2048
	ds_read_b64_tr_b16 v[68:69], v108 offset:3072
	s_waitcnt lgkmcnt(6)
	v_mfma_f32_32x32x16_bf16 v[16:31], v[16:19], v[36:39], 0
	v_add_f32_e64 v70, v32, v32
	v_add_f32_e64 v71, v32, v33
	v_add_f32_e32 v3, v7, v75
	v_add_f32_e32 v7, v72, v78
	v_mov_b32_e32 v9, v71
	v_cvt_pk_bf16_f32 v70, v59, v12
	v_cvt_pk_bf16_f32 v71, v11, v54
	v_cvt_pk_bf16_f32 v72, v72, v6
	s_waitcnt lgkmcnt(4)
	v_mfma_f32_32x32x16_bf16 v[32:47], v[40:43], v[36:39], 0
	v_cvt_pk_bf16_f32 v73, v15, v48
	v_add_f32_e64 v60, v60, v8
	v_add_f32_e64 v61, v61, v9
	v_add_f32_e32 v13, v59, v76
	v_add_f32_e32 v61, v60, v61
	v_add_f32_e32 v60, v60, v60
	v_mov_b32_e32 v59, v61
	v_add_f32_e32 v57, v5, v74
	v_add_f32_e32 v56, v56, v58
	v_add_f32_e32 v57, v57, v59
	s_waitcnt lgkmcnt(2)
	v_mfma_f32_32x32x16_bf16 v[16:31], v[62:65], v[70:73], v[16:31]
	ds_read_b64_tr_b16 v[60:61], v107 offset:4096
	ds_read_b64_tr_b16 v[62:63], v107 offset:5120
	v_add_f32_e32 v57, v56, v57
	v_add_f32_e32 v56, v56, v56
	v_add_f32_e32 v49, v15, v79
	v_mov_b32_e32 v15, v57
	v_cvt_pk_bf16_f32 v56, v51, v0
	v_cvt_pk_bf16_f32 v57, v53, v8
	v_cvt_pk_bf16_f32 v58, v74, v58
	s_waitcnt lgkmcnt(2)
	v_mfma_f32_32x32x16_bf16 v[32:47], v[66:69], v[70:73], v[32:47]
	ds_read_b64_tr_b16 v[64:65], v108 offset:4096
	ds_read_b64_tr_b16 v[66:67], v108 offset:5120
	ds_read_b64_tr_b16 v[68:69], v107 offset:6144
	ds_read_b64_tr_b16 v[70:71], v107 offset:7168
	v_cvt_pk_bf16_f32 v59, v75, v14
	v_add_f32_e32 v2, v2, v14
	v_add_f32_e32 v3, v3, v15
	v_add_f32_e32 v55, v11, v77
	v_add_f32_e32 v3, v2, v3
	v_add_f32_e32 v2, v2, v2
	v_mov_b32_e32 v5, v3
	v_add_f32_e32 v2, v12, v4
	v_add_f32_e32 v3, v13, v5
	s_waitcnt lgkmcnt(4)
	v_mfma_f32_32x32x16_bf16 v[16:31], v[60:63], v[56:59], v[16:31]
	ds_read_b64_tr_b16 v[12:13], v108 offset:6144
	ds_read_b64_tr_b16 v[14:15], v108 offset:7168
	v_add_f32_e32 v3, v2, v3
	v_add_f32_e32 v2, v2, v2
	v_mov_b32_e32 v51, v3
	v_add_f32_e32 v2, v54, v50
	v_add_f32_e32 v3, v55, v51
	v_cvt_pk_bf16_f32 v54, v76, v4
	v_cvt_pk_bf16_f32 v55, v77, v50
	v_add_f32_e32 v3, v2, v3
	v_add_f32_e32 v2, v2, v2
	s_waitcnt lgkmcnt(4)
	v_mfma_f32_32x32x16_bf16 v[32:47], v[64:67], v[56:59], v[32:47]
	v_cvt_pk_bf16_f32 v56, v78, v10
	v_cvt_pk_bf16_f32 v57, v79, v52
	v_mov_b32_e32 v11, v3
	v_add_f32_e64 v2, v6, v10
	v_add_f32_e64 v3, v7, v11
	s_cmp_lt_u32 s38, 16
	v_add_f32_e32 v3, v2, v3
	v_add_f32_e32 v2, v2, v2
	v_mov_b32_e32 v53, v3
	s_waitcnt lgkmcnt(2)
	v_mfma_f32_32x32x16_bf16 v[16:31], v[68:71], v[54:57], v[16:31]
	v_add_f32_e64 v2, v48, v52
	v_add_f32_e64 v3, v49, v53
	v_add_f32_e32 v0, v2, v3
	v_add_f32_e32 v3, 0, v0
	s_waitcnt lgkmcnt(0)
	v_mfma_f32_32x32x16_bf16 v[32:47], v[12:15], v[54:57], v[32:47]
	s_cbranch_scc1 .LBB0_899
; #define LAS __attribute__((address_space(3)))
; #define MFMA32(a, b, c) __builtin_amdgcn_mfma_f32_32x32x16_bf16((a), (b), (c), 0, 0, 0)
; __device__ __forceinline__ void qk_tile(f32x16& p0, f32x16& p1, LAS const unsigned char* Kt, const bf16x8 (&qf)[4], int lane) {
;     LAS const unsigned char* kp = Kt + (lane & 31) * KVP + 16 * (lane >> 5);
;     f32x16 z = {}; p0 = z; p1 = z;
; #pragma unroll
;     for (int s = 0; s < 4; ++s) { const bf16x8 a0 = *(LAS const bf16x8*)(kp + 32 * s), a1 = *(LAS const bf16x8*)(kp + 32 * KVP + 32 * s);
;         p0 = MFMA32(a0, qf[s], p0); p1 = MFMA32(a1, qf[s], p1); }
; }
	ds_read_b128 v[4:7], v89 offset:58368
	ds_read_b128 v[8:11], v89 offset:58400
	v_add_u32_e32 v0, 0xfffffbe1, v178
	v_sub_u32_e32 v2, v0, v90
	s_waitcnt lgkmcnt(1)
	v_mfma_f32_32x32x16_bf16 v[48:63], v[4:7], v[144:147], 0
	ds_read_b128 v[4:7], v89 offset:62976
	ds_read_b128 v[12:15], v89 offset:63008
	s_waitcnt lgkmcnt(1)
	v_mfma_f32_32x32x16_bf16 v[64:79], v[4:7], v[144:147], 0
	v_mfma_f32_32x32x16_bf16 v[48:63], v[8:11], v[148:151], v[48:63]
	ds_read_b128 v[4:7], v89 offset:58432
	ds_read_b128 v[8:11], v89 offset:58464
	ds_read_b128 v[108:111], v89 offset:63040
	ds_read_b128 v[112:115], v89 offset:63072
	v_med3_i32 v89, v2, -1, v170
	v_med3_i32 v2, v2, s86, v171
	v_lshl_add_u32 v2, v2, 2, s96
	v_lshl_add_u32 v89, v89, 2, s96
	v_add_u32_e32 v2, 0xfffff900, v2
	s_waitcnt lgkmcnt(4)
	v_mfma_f32_32x32x16_bf16 v[64:79], v[12:15], v[148:151], v[64:79]
	v_sub_u32_e32 v12, v0, v91
	v_med3_i32 v13, v12, -1, v170
	v_med3_i32 v12, v12, s86, v171
	v_lshl_add_u32 v13, v13, 2, s96
	v_sub_u32_e32 v15, v0, v96
	s_waitcnt lgkmcnt(3)
	v_mfma_f32_32x32x16_bf16 v[48:63], v[4:7], v[152:155], v[48:63]
	v_sub_u32_e32 v5, v0, v92
	v_sub_u32_e32 v7, v0, v93
	v_lshl_add_u32 v4, v12, 2, s96
	v_med3_i32 v6, v5, -1, v170
	v_med3_i32 v5, v5, s86, v171
	v_med3_i32 v12, v7, -1, v170
	v_med3_i32 v7, v7, s86, v171
	s_waitcnt lgkmcnt(1)
	v_mfma_f32_32x32x16_bf16 v[64:79], v[108:111], v[152:155], v[64:79]
	v_lshl_add_u32 v5, v5, 2, s96
	v_lshl_add_u32 v7, v7, 2, s96
	v_add_u32_e32 v4, 0xfffff900, v4
	v_lshl_add_u32 v6, v6, 2, s96
	v_add_u32_e32 v5, 0xfffff900, v5
	v_add_u32_e32 v7, 0xfffff900, v7
	v_lshl_add_u32 v12, v12, 2, s96
	v_mfma_f32_32x32x16_bf16 v[48:63], v[8:11], v[156:159], v[48:63]
	ds_read_b32 v8, v89 offset:256
	ds_read_b32 v2, v2
	ds_read_b32 v9, v13 offset:256
	ds_read_b32 v4, v4
	ds_read_b32 v6, v6 offset:256
	ds_read_b32 v5, v5
	ds_read_b32 v10, v12 offset:256
	ds_read_b32 v7, v7
	v_sub_u32_e32 v13, v0, v95
	v_med3_i32 v14, v13, -1, v170
	v_med3_i32 v13, v13, s86, v171
	v_lshl_add_u32 v13, v13, 2, s96
	v_lshl_add_u32 v14, v14, 2, s96
	v_add_u32_e32 v13, 0xfffff900, v13
	s_waitcnt lgkmcnt(8)
	v_mfma_f32_32x32x16_bf16 v[64:79], v[112:115], v[156:159], v[64:79]
	s_waitcnt lgkmcnt(5)
	v_add_f32_e32 v9, v49, v9
	v_sub_u32_e32 v49, v0, v97
	v_add_f32_e32 v8, v48, v8
	s_waitcnt lgkmcnt(3)
	v_add_f32_e32 v6, v50, v6
	v_med3_i32 v48, v15, -1, v170
	v_med3_i32 v15, v15, s86, v171
	v_med3_i32 v50, v49, -1, v170
	s_nop 2
	v_add_f32_e32 v11, v64, v2
	v_sub_u32_e32 v2, v0, v94
	v_med3_i32 v12, v2, -1, v170
	v_med3_i32 v2, v2, s86, v171
	v_med3_i32 v49, v49, s86, v171
	v_lshl_add_u32 v2, v2, 2, s96
	v_lshl_add_u32 v15, v15, 2, s96
	v_lshl_add_u32 v49, v49, 2, s96
	v_lshl_add_u32 v12, v12, 2, s96
	v_add_u32_e32 v2, 0xfffff900, v2
	v_lshl_add_u32 v48, v48, 2, s96
	v_add_u32_e32 v15, 0xfffff900, v15
	v_lshl_add_u32 v50, v50, 2, s96
	v_add_u32_e32 v49, 0xfffff900, v49
	ds_read_b32 v12, v12 offset:256
	ds_read_b32 v2, v2
	ds_read_b32 v14, v14 offset:256
	ds_read_b32 v13, v13
	ds_read_b32 v48, v48 offset:256
	ds_read_b32 v15, v15
	ds_read_b32 v50, v50 offset:256
	ds_read_b32 v49, v49
	v_add_f32_e32 v4, v65, v4
	s_waitcnt lgkmcnt(9)
	v_add_f32_e32 v10, v51, v10
	s_waitcnt lgkmcnt(7)
	v_add_f32_e32 v12, v52, v12
	s_waitcnt lgkmcnt(6)
	v_add_f32_e32 v52, v68, v2
	s_waitcnt lgkmcnt(3)
	v_add_f32_e32 v48, v54, v48
	v_sub_u32_e32 v2, v0, v98
	v_sub_u32_e32 v51, v0, v99
	v_sub_u32_e32 v54, v0, v100
	v_sub_u32_e32 v65, v0, v101
	v_add_f32_e32 v5, v66, v5
	v_add_f32_e32 v14, v53, v14
	s_waitcnt lgkmcnt(1)
	v_add_f32_e32 v55, v55, v50
	v_med3_i32 v50, v2, -1, v170
	v_med3_i32 v2, v2, s86, v171
	v_med3_i32 v53, v51, -1, v170
	v_med3_i32 v51, v51, s86, v171
	v_med3_i32 v64, v54, -1, v170
	v_med3_i32 v54, v54, s86, v171
	v_med3_i32 v66, v65, -1, v170
	v_med3_i32 v65, v65, s86, v171
	v_lshl_add_u32 v2, v2, 2, s96
	v_lshl_add_u32 v51, v51, 2, s96
	v_lshl_add_u32 v54, v54, 2, s96
	v_lshl_add_u32 v65, v65, 2, s96
	v_lshl_add_u32 v50, v50, 2, s96
	v_add_u32_e32 v2, 0xfffff900, v2
	v_lshl_add_u32 v53, v53, 2, s96
	v_add_u32_e32 v51, 0xfffff900, v51
	v_lshl_add_u32 v64, v64, 2, s96
	v_add_u32_e32 v54, 0xfffff900, v54
	v_lshl_add_u32 v66, v66, 2, s96
	v_add_u32_e32 v65, 0xfffff900, v65
	ds_read_b32 v50, v50 offset:256
	ds_read_b32 v2, v2
	ds_read_b32 v53, v53 offset:256
	ds_read_b32 v51, v51
	ds_read_b32 v64, v64 offset:256
	ds_read_b32 v54, v54
	ds_read_b32 v66, v66 offset:256
	ds_read_b32 v65, v65
	v_add_f32_e32 v7, v67, v7
	s_waitcnt lgkmcnt(6)
	v_add_f32_e32 v67, v72, v2
	s_waitcnt lgkmcnt(4)
	v_add_f32_e32 v68, v73, v51
	s_waitcnt lgkmcnt(3)
	v_add_f32_e32 v58, v58, v64
	s_waitcnt lgkmcnt(2)
	v_add_f32_e32 v64, v74, v54
	v_sub_u32_e32 v2, v0, v102
	v_sub_u32_e32 v51, v0, v103
	v_sub_u32_e32 v54, v0, v104
	v_sub_u32_e32 v0, v0, v105
	v_add_f32_e32 v13, v69, v13
	v_add_f32_e32 v56, v56, v50
	v_add_f32_e32 v57, v57, v53
	s_waitcnt lgkmcnt(1)
	v_add_f32_e32 v59, v59, v66
	v_med3_i32 v50, v2, -1, v170
	v_med3_i32 v2, v2, s86, v171
	v_med3_i32 v53, v51, -1, v170
	v_med3_i32 v51, v51, s86, v171
	v_med3_i32 v66, v54, -1, v170
	v_med3_i32 v54, v54, s86, v171
	v_med3_i32 v69, v0, -1, v170
	v_med3_i32 v0, v0, s86, v171
	v_lshl_add_u32 v2, v2, 2, s96
	v_lshl_add_u32 v51, v51, 2, s96
	v_lshl_add_u32 v54, v54, 2, s96
	v_lshl_add_u32 v0, v0, 2, s96
	v_lshl_add_u32 v50, v50, 2, s96
	v_add_u32_e32 v2, 0xfffff900, v2
	v_lshl_add_u32 v53, v53, 2, s96
	v_add_u32_e32 v51, 0xfffff900, v51
	v_lshl_add_u32 v66, v66, 2, s96
	v_add_u32_e32 v54, 0xfffff900, v54
	v_lshl_add_u32 v69, v69, 2, s96
	v_add_u32_e32 v0, 0xfffff900, v0
	ds_read_b32 v50, v50 offset:256
	ds_read_b32 v2, v2
	ds_read_b32 v53, v53 offset:256
	ds_read_b32 v51, v51
	ds_read_b32 v66, v66 offset:256
	ds_read_b32 v54, v54
	ds_read_b32 v69, v69 offset:256
	ds_read_b32 v0, v0
	v_add_f32_e32 v15, v70, v15
	v_add_f32_e32 v49, v71, v49
	s_waitcnt lgkmcnt(7)
; __device__ __forceinline__ float xor32_other(float x, int h) { auto r = __builtin_amdgcn_permlane32_swap(__float_as_uint(x), __float_as_uint(x), false, false); return __uint_as_float(h ? r[0] : r[1]); }
; __device__ __forceinline__ float xor32_max(float x) { auto r = __builtin_amdgcn_permlane32_swap(__float_as_uint(x), __float_as_uint(x), false, false); return __builtin_fmaxf(__uint_as_float(r[0]), __uint_as_float(r[1])); }
	v_add_f32_e32 v70, v60, v50
	s_waitcnt lgkmcnt(1)
	v_add_f32_e32 v63, v63, v69
	s_waitcnt lgkmcnt(0)
	v_add_f32_e32 v69, v79, v0
	v_max_f32_e32 v0, v9, v4
	v_add_f32_e32 v71, v76, v2
	v_max3_f32 v0, v8, v11, v0
	v_max_f32_e32 v2, v6, v5
	v_max_f32_e32 v50, v10, v7
	v_max3_f32 v0, v0, v2, v50
	v_max_f32_e32 v2, v12, v52
	v_max_f32_e32 v50, v14, v13
	v_max3_f32 v0, v0, v2, v50
	v_max_f32_e32 v2, v48, v15
	v_max_f32_e32 v50, v55, v49
	v_add_f32_e32 v65, v75, v65
	v_max3_f32 v0, v0, v2, v50
	v_max_f32_e32 v2, v56, v67
	v_max_f32_e32 v50, v57, v68
	v_add_f32_e32 v72, v61, v53
	v_add_f32_e32 v73, v77, v51
	v_max3_f32 v0, v0, v2, v50
	v_max_f32_e32 v2, v58, v64
	v_max_f32_e32 v50, v59, v65
	v_add_f32_e32 v62, v62, v66
	v_add_f32_e32 v74, v78, v54
	v_max3_f32 v0, v0, v2, v50
	v_max_f32_e32 v2, v70, v71
	v_max_f32_e32 v50, v72, v73
	v_max3_f32 v0, v0, v2, v50
	v_max_f32_e32 v2, v62, v74
	v_max_f32_e32 v50, v63, v69
	v_max3_f32 v0, v0, v2, v50
	v_mov_b32_e32 v2, v0
	s_nop 1
	v_permlane32_swap_b32_e32 v0, v2
	v_max_f32_e32 v0, v0, v2
	v_max3_f32 v66, v81, v0, s55
	v_sub_f32_e32 v0, v81, v66
	v_exp_f32_e32 v2, v0
	v_sub_f32_e32 v0, v8, v66
	v_exp_f32_e32 v75, v0
	v_sub_f32_e32 v0, v11, v66
	v_exp_f32_e32 v92, v0
	v_sub_f32_e32 v0, v9, v66
	v_exp_f32_e32 v50, v0
	v_sub_f32_e32 v0, v4, v66
	v_sub_f32_e32 v4, v10, v66
	v_sub_f32_e32 v6, v6, v66
	v_sub_f32_e32 v5, v5, v66
	v_exp_f32_e32 v60, v4
	v_sub_f32_e32 v4, v7, v66
	v_exp_f32_e32 v76, v6
	v_exp_f32_e32 v93, v5
	v_sub_f32_e32 v5, v12, v66
	v_exp_f32_e32 v6, v4
	v_sub_f32_e32 v4, v14, v66
	v_exp_f32_e32 v77, v5
	v_sub_f32_e32 v5, v52, v66
	v_exp_f32_e32 v52, v4
	v_sub_f32_e32 v4, v13, v66
	v_sub_f32_e32 v10, v58, v66
	v_exp_f32_e32 v54, v4
	v_sub_f32_e32 v4, v55, v66
	v_exp_f32_e32 v55, v10
	v_sub_f32_e32 v10, v64, v66
	v_exp_f32_e32 v95, v10
	v_sub_f32_e32 v10, v68, v66
	v_exp_f32_e32 v94, v5
	v_sub_f32_e32 v5, v48, v66
	v_sub_f32_e32 v8, v56, v66
	v_exp_f32_e32 v14, v10
	v_sub_f32_e32 v10, v59, v66
	v_sub_f32_e32 v56, v62, v66
	v_sub_f32_e32 v62, v69, v66
	v_add_f32_e32 v68, v75, v50
	v_add_f32_e32 v69, v76, v60
	v_exp_f32_e32 v7, v5
	v_exp_f32_e32 v4, v4
	v_sub_f32_e32 v11, v70, v66
	v_exp_f32_e32 v48, v10
	v_sub_f32_e32 v10, v65, v66
	v_exp_f32_e32 v65, v56
	v_sub_f32_e32 v56, v74, v66
	v_add_f32_e32 v68, v68, v69
	v_mov_b32_e32 v69, v60
	v_mov_b32_e32 v70, v60
	v_exp_f32_e32 v97, v56
	v_sub_f32_e32 v56, v73, v66
	v_permlane32_swap_b32_e32 v69, v70
	v_exp_f32_e32 v58, v56
	v_sub_f32_e32 v56, v63, v66
	v_mul_f32_e32 v63, v2, v106
	v_cndmask_b32_e64 v69, v69, v70, s[4:5]
	v_exp_f32_e32 v13, v8
	v_sub_f32_e32 v8, v67, v66
	v_cndmask_b32_e64 v63, v69, v63, s[4:5]
	v_exp_f32_e32 v67, v8
	v_sub_f32_e32 v8, v49, v66
	v_add_f32_e32 v63, v68, v63
	v_add_f32_e32 v68, v77, v52
	v_add_f32_e32 v70, v7, v4
	v_exp_f32_e32 v12, v8
	v_sub_f32_e32 v8, v57, v66
	v_exp_f32_e32 v59, v11
	v_sub_f32_e32 v11, v71, v66
	v_add_f32_e32 v68, v68, v70
	v_mov_b32_e32 v70, v4
	v_mov_b32_e32 v71, v4
	v_exp_f32_e32 v8, v8
	s_nop 0
	v_permlane32_swap_b32_e32 v70, v71
	v_cndmask_b32_e64 v70, v70, v71, s[4:5]
	v_cndmask_b32_e64 v69, v70, v69, s[4:5]
	v_add_f32_e32 v68, v69, v68
	v_exp_f32_e32 v64, v10
	v_sub_f32_e32 v10, v72, v66
	ds_write2_b32 v88, v63, v68 offset0:16 offset1:18
	v_add_f32_e32 v63, v13, v8
	v_add_f32_e32 v68, v55, v48
	v_exp_f32_e32 v10, v10
	v_exp_f32_e32 v56, v56
	v_add_f32_e32 v63, v63, v68
	v_mov_b32_e32 v68, v48
	v_mov_b32_e32 v69, v48
	s_nop 1
	v_permlane32_swap_b32_e32 v68, v69
	v_cndmask_b32_e64 v68, v68, v69, s[4:5]
	v_cndmask_b32_e64 v69, v68, v70, s[4:5]
	v_add_f32_e32 v63, v63, v69
	v_add_f32_e32 v69, v59, v10
	v_add_f32_e32 v70, v65, v56
	v_add_f32_e32 v69, v69, v70
	v_mov_b32_e32 v70, v56
	v_mov_b32_e32 v71, v56
	v_exp_f32_e32 v0, v0
	s_nop 0
	v_permlane32_swap_b32_e32 v70, v71
	v_cndmask_b32_e64 v70, v70, v71, s[4:5]
	v_cndmask_b32_e64 v68, v70, v68, s[4:5]
	v_add_f32_e32 v68, v69, v68
	v_sub_f32_e32 v5, v15, v66
	ds_write2_b32 v88, v63, v68 offset0:20 offset1:22
	v_add_f32_e32 v63, v92, v0
	v_add_f32_e32 v68, v93, v6
	v_exp_f32_e32 v15, v5
	v_add_f32_e32 v63, v63, v68
	v_mov_b32_e32 v68, v6
	v_mov_b32_e32 v69, v6
	s_nop 1
	v_permlane32_swap_b32_e32 v68, v69
	v_cndmask_b32_e64 v68, v68, v69, s[4:5]
	v_cndmask_b32_e64 v69, v68, v70, s[4:5]
	v_add_f32_e32 v63, v63, v69
	v_add_f32_e32 v69, v94, v54
	v_add_f32_e32 v70, v15, v12
	v_add_f32_e32 v69, v69, v70
	v_mov_b32_e32 v70, v12
	v_mov_b32_e32 v71, v12
	s_nop 1
	v_permlane32_swap_b32_e32 v70, v71
	v_cndmask_b32_e64 v70, v70, v71, s[4:5]
	v_cndmask_b32_e64 v68, v70, v68, s[4:5]
	v_add_f32_e32 v68, v69, v68
	ds_write2_b32 v88, v63, v68 offset0:24 offset1:26
	v_add_f32_e32 v63, v67, v14
	v_add_f32_e32 v68, v95, v64
	v_exp_f32_e32 v96, v11
	v_exp_f32_e32 v62, v62
	v_add_f32_e32 v63, v63, v68
	v_mov_b32_e32 v68, v64
	v_mov_b32_e32 v69, v64
	s_nop 1
	v_permlane32_swap_b32_e32 v68, v69
	v_cndmask_b32_e64 v68, v68, v69, s[4:5]
	v_cndmask_b32_e64 v69, v68, v70, s[4:5]
	v_add_f32_e32 v63, v63, v69
	v_add_f32_e32 v69, v96, v58
	v_add_f32_e32 v70, v97, v62
	v_add_f32_e32 v69, v69, v70
	v_mov_b32_e32 v70, v62
	v_mov_b32_e32 v71, v62
	s_nop 1
	v_permlane32_swap_b32_e32 v70, v71
	v_cndmask_b32_e64 v70, v70, v71, s[4:5]
	v_cndmask_b32_e64 v68, v70, v68, s[4:5]
	v_add_f32_e32 v68, v69, v68
	ds_write2_b32 v88, v63, v68 offset0:28 offset1:30
	v_add_u32_e32 v63, s82, v128
	v_add3_u32 v98, v63, v181, v180
	v_add_f32_e32 v51, v75, v92
	v_cvt_pk_bf16_f32 v68, v75, v50
	ds_read_b64_tr_b16 v[72:73], v98
	ds_read_b64_tr_b16 v[74:75], v98 offset:1024
	v_add_u32_e32 v63, v63, v182
	v_add_f32_e32 v61, v76, v93
	v_add_f32_e32 v53, v77, v94
	v_cvt_pk_bf16_f32 v69, v76, v60
	v_cvt_pk_bf16_f32 v70, v77, v52
	ds_read_b64_tr_b16 v[76:77], v63
	ds_read_b64_tr_b16 v[78:79], v63 offset:1024
	ds_read_b64_tr_b16 v[88:89], v98 offset:2048
	ds_read_b64_tr_b16 v[90:91], v98 offset:3072
	v_mul_f32_e32 v30, v30, v2
	v_mul_f32_e32 v31, v31, v2
	v_mul_f32_e32 v28, v28, v2
	v_mul_f32_e32 v29, v29, v2
	v_mul_f32_e32 v26, v26, v2
	v_mul_f32_e32 v27, v27, v2
	v_mul_f32_e32 v24, v24, v2
	v_mul_f32_e32 v25, v25, v2
	v_mul_f32_e32 v22, v22, v2
	v_mul_f32_e32 v23, v23, v2
	v_mul_f32_e32 v20, v20, v2
	v_mul_f32_e32 v21, v21, v2
	v_mul_f32_e32 v18, v18, v2
	v_mul_f32_e32 v19, v19, v2
	v_mul_f32_e32 v16, v16, v2
	v_mul_f32_e32 v17, v17, v2
	v_mul_f32_e32 v46, v46, v2
	v_mul_f32_e32 v47, v47, v2
	v_mul_f32_e32 v44, v44, v2
	v_mul_f32_e32 v45, v45, v2
	v_mul_f32_e32 v42, v42, v2
	v_mul_f32_e32 v43, v43, v2
	v_mul_f32_e32 v40, v40, v2
	v_mul_f32_e32 v41, v41, v2
	v_mul_f32_e32 v38, v38, v2
	v_mul_f32_e32 v39, v39, v2
	v_cvt_pk_bf16_f32 v71, v7, v4
	v_mul_f32_e32 v36, v36, v2
	v_mul_f32_e32 v37, v37, v2
	v_mul_f32_e32 v34, v34, v2
	v_mul_f32_e32 v35, v35, v2
	v_mul_f32_e32 v32, v32, v2
	v_mul_f32_e32 v33, v33, v2
	s_waitcnt lgkmcnt(4)
; __device__ __forceinline__ unsigned cvt_pk_bf16(float lo, float hi) { f32x2 v = {lo, hi}; bf16x2_t b = __builtin_convertvector(v, bf16x2_t); return __builtin_bit_cast(unsigned, b); }
; __device__ __forceinline__ s16x4 vtr(lds_cptr p){ return __builtin_bit_cast(s16x4,__builtin_amdgcn_ds_read_tr16_b64_v4i16((__attribute__((address_space(3))) v4i16_t*)p)); }
; #define LAS __attribute__((address_space(3)))
; #define MFMA32(a, b, c) __builtin_amdgcn_mfma_f32_32x32x16_bf16((a), (b), (c), 0, 0, 0)
; __device__ __forceinline__ s16x4 vtr(LAS const unsigned char* p) { return __builtin_bit_cast(s16x4, __builtin_amdgcn_ds_read_tr16_b64_v4i16((LAS v4i16_t*)p)); }
; __device__ __forceinline__ void pv_tile(f32x16& o0, f32x16& o1, LAS const unsigned char* Vt, const bf16x8 (&pf)[4], int lane) {
;     const int q = (lane & 15) >> 2, swz = ((q >> 1) & 1) * 64;
;     LAS const unsigned char* vp0 = Vt + (4 * (lane >> 5) + q) * 128 + (((16 * ((lane >> 4) & 1) + 4 * (lane & 3)) * 2) ^ swz);
;     LAS const unsigned char* vp1 = Vt + (4 * (lane >> 5) + q) * 128 + (((16 * ((lane >> 4) & 1) + 4 * (lane & 3)) * 2 + 64) ^ swz);
; #pragma unroll
;     for (int s = 0; s < 4; ++s) {
;         const s16x4 l0 = vtr(vp0 + (16 * s) * 128), h0 = vtr(vp0 + (16 * s + 8) * 128), l1 = vtr(vp1 + (16 * s) * 128), h1 = vtr(vp1 + (16 * s + 8) * 128);
;         const bf16x8 v0 = {l0[0], l0[1], l0[2], l0[3], h0[0], h0[1], h0[2], h0[3]}, v1 = {l1[0], l1[1], l1[2], l1[3], h1[0], h1[1], h1[2], h1[3]};
;         o0 = MFMA32(v0, pf[s], o0); o1 = MFMA32(v1, pf[s], o1); }
; }
; __device__ __forceinline__ void pack_p(bf16x8 (&pf)[4], const f32x16& p0, const f32x16& p1) {
; #pragma unroll
;     for (int s = 0; s < 4; ++s) { const f32x16& p = (s < 2) ? p0 : p1; const int b = 8 * (s & 1);
;         u32x4 w; w.x = cvt_pk_bf16(p[b], p[b + 1]); w.y = cvt_pk_bf16(p[b + 2], p[b + 3]); w.z = cvt_pk_bf16(p[b + 4], p[b + 5]); w.w = cvt_pk_bf16(p[b + 6], p[b + 7]);
;         pf[s] = __builtin_bit_cast(bf16x8, w); }
; }
	v_mfma_f32_32x32x16_bf16 v[16:31], v[72:75], v[68:71], v[16:31]
	ds_read_b64_tr_b16 v[72:73], v63 offset:2048
	ds_read_b64_tr_b16 v[74:75], v63 offset:3072
	v_add_f32_e64 v50, v50, v0
	v_add_f32_e64 v51, v51, v1
	v_add_f32_e32 v5, v7, v15
	v_add_f32_e32 v51, v50, v51
	v_add_f32_e32 v50, v50, v50
	v_mov_b32_e32 v7, v51
	v_add_f32_e32 v50, v60, v6
	v_add_f32_e32 v51, v61, v7
	v_add_f32_e32 v49, v55, v95
	s_waitcnt lgkmcnt(4)
	v_mfma_f32_32x32x16_bf16 v[32:47], v[76:79], v[68:71], v[32:47]
	v_cvt_pk_bf16_f32 v68, v13, v8
	v_cvt_pk_bf16_f32 v69, v55, v48
	v_cvt_pk_bf16_f32 v70, v59, v10
	v_cvt_pk_bf16_f32 v71, v65, v56
	v_add_f32_e32 v51, v50, v51
	v_add_f32_e32 v50, v50, v50
	v_mov_b32_e32 v55, v51
	ds_read_b64_tr_b16 v[76:77], v98 offset:4096
	ds_read_b64_tr_b16 v[78:79], v98 offset:5120
	s_waitcnt lgkmcnt(4)
	v_mfma_f32_32x32x16_bf16 v[16:31], v[88:91], v[68:71], v[16:31]
	v_add_f32_e64 v50, v52, v54
	v_add_f32_e64 v51, v53, v55
	v_add_f32_e32 v9, v13, v67
	v_add_f32_e32 v51, v50, v51
	v_add_f32_e32 v50, v50, v50
	v_mov_b32_e32 v13, v51
	v_cvt_pk_bf16_f32 v50, v92, v0
	v_cvt_pk_bf16_f32 v51, v93, v6
	v_cvt_pk_bf16_f32 v52, v94, v54
	s_waitcnt lgkmcnt(2)
	v_mfma_f32_32x32x16_bf16 v[32:47], v[72:75], v[68:71], v[32:47]
	ds_read_b64_tr_b16 v[68:69], v63 offset:4096
	ds_read_b64_tr_b16 v[70:71], v63 offset:5120
	ds_read_b64_tr_b16 v[72:73], v98 offset:6144
	ds_read_b64_tr_b16 v[74:75], v98 offset:7168
	v_cvt_pk_bf16_f32 v53, v15, v12
	v_add_f32_e32 v4, v4, v12
	v_add_f32_e32 v5, v5, v13
	v_add_f32_e32 v57, v65, v97
	v_add_f32_e32 v5, v4, v5
	v_add_f32_e32 v4, v4, v4
	v_mov_b32_e32 v15, v5
	v_add_f32_e32 v4, v8, v14
	v_add_f32_e32 v5, v9, v15
	s_waitcnt lgkmcnt(4)
	v_mfma_f32_32x32x16_bf16 v[16:31], v[76:79], v[50:53], v[16:31]
	v_add_f32_e64 v8, v4, v4
	v_add_f32_e64 v9, v4, v5
	ds_read_b64_tr_b16 v[4:5], v63 offset:6144
	ds_read_b64_tr_b16 v[6:7], v63 offset:7168
	v_mov_b32_e32 v65, v9
	v_add_f32_e32 v8, v48, v64
	v_add_f32_e32 v9, v49, v65
	v_cvt_pk_bf16_f32 v12, v67, v14
	v_add_f32_e32 v9, v8, v9
	v_add_f32_e32 v8, v8, v8
	v_cvt_pk_bf16_f32 v13, v95, v64
	s_waitcnt lgkmcnt(4)
	v_mfma_f32_32x32x16_bf16 v[32:47], v[68:71], v[50:53], v[32:47]
	v_cvt_pk_bf16_f32 v14, v96, v58
	v_cvt_pk_bf16_f32 v15, v97, v62
	v_add_f32_e32 v11, v59, v96
	v_mov_b32_e32 v59, v9
	v_add_f32_e64 v8, v10, v58
	v_add_f32_e64 v9, v11, v59
	v_add_f32_e32 v9, v8, v9
	v_add_f32_e32 v8, v8, v8
	s_waitcnt lgkmcnt(2)
	v_mfma_f32_32x32x16_bf16 v[16:31], v[72:75], v[12:15], v[16:31]
	v_mov_b32_e32 v63, v9
	v_add_f32_e64 v8, v56, v62
	v_add_f32_e64 v9, v57, v63
	v_add_f32_e32 v0, v8, v9
	v_fmac_f32_e32 v0, v3, v2
	v_mov_b32_e32 v3, v0
	s_waitcnt lgkmcnt(0)
	v_mfma_f32_32x32x16_bf16 v[32:47], v[4:7], v[12:15], v[32:47]
	s_branch .LBB0_900

; __device__ __forceinline__ s16x4 vtr(lds_cptr p){ return __builtin_bit_cast(s16x4,__builtin_amdgcn_ds_read_tr16_b64_v4i16((__attribute__((address_space(3))) v4i16_t*)p)); }
; #define LAS __attribute__((address_space(3)))
; __device__ __forceinline__ s16x4 vtr(LAS const unsigned char* p) { return __builtin_bit_cast(s16x4, __builtin_amdgcn_ds_read_tr16_b64_v4i16((LAS v4i16_t*)p)); }
; __device__ __forceinline__ void pv_tile(f32x16& o0, f32x16& o1, LAS const unsigned char* Vt, const bf16x8 (&pf)[4], int lane) {
;     const int q = (lane & 15) >> 2, swz = ((q >> 1) & 1) * 64;
;     LAS const unsigned char* vp0 = Vt + (4 * (lane >> 5) + q) * 128 + (((16 * ((lane >> 4) & 1) + 4 * (lane & 3)) * 2) ^ swz);
;     LAS const unsigned char* vp1 = Vt + (4 * (lane >> 5) + q) * 128 + (((16 * ((lane >> 4) & 1) + 4 * (lane & 3)) * 2 + 64) ^ swz);
; #pragma unroll
;     for (int s = 0; s < 4; ++s) {
;         const s16x4 l0 = vtr(vp0 + (16 * s) * 128), h0 = vtr(vp0 + (16 * s + 8) * 128), l1 = vtr(vp1 + (16 * s) * 128), h1 = vtr(vp1 + (16 * s + 8) * 128);
.LBB0_965:
	v_add_u32_e32 v10, s50, v188
	v_add3_u32 v114, v10, v181, v180
	v_add_u32_e32 v115, v10, v182
	ds_read_b64_tr_b16 v[6:7], v114 offset:8192
	ds_read_b64_tr_b16 v[8:9], v114 offset:9216
	ds_read_b64_tr_b16 v[10:11], v115 offset:8192
	ds_read_b64_tr_b16 v[12:13], v115 offset:9216
	s_nop 2
	v_max_f32_e32 v2, v97, v97
	v_max_f32_e32 v3, v96, v96
	v_max_f32_e32 v2, v3, v2
	v_max3_f32 v3, v98, v99, v81
	v_max3_f32 v2, v2, v80, v82
	v_max3_f32 v2, v2, v83, v100
	v_max3_f32 v3, v3, v102, v103
	v_max3_f32 v2, v2, v101, v84
	v_max3_f32 v3, v3, v86, v87
	v_max3_f32 v2, v2, v85, v104
	v_max3_f32 v3, v3, v106, v107
	v_max3_f32 v2, v2, v105, v88
	v_max3_f32 v3, v3, v90, v91
	v_max3_f32 v2, v2, v89, v108
	v_max3_f32 v3, v3, v110, v111
	v_max3_f32 v2, v2, v109, v92
	v_max3_f32 v3, v3, v94, v95
	v_max3_f32 v2, v2, v93, v3
	v_mov_b32_e32 v3, v2
	s_nop 1
	v_permlane32_swap_b32_e32 v2, v3
	s_xor_b64 s[6:7], s[62:63], -1
	v_max_f32_e32 v2, v2, v3
	v_cndmask_b32_e64 v3, 0, 1, s[6:7]
	v_cmp_ne_u32_e64 s[4:5], 1, v3
	s_andn2_b64 vcc, exec, s[6:7]
	s_mov_b64 s[6:7], -1
	s_cbranch_vccnz .LBB0_968
	v_cmp_lt_f32_e32 vcc, s91, v2
	s_cbranch_vccz .LBB0_974
	s_nop 0
	v_cndmask_b32_e32 v2, 0, v2, vcc

.LBB0_979:
	s_nop 9
	v_max_f32_e32 v0, v97, v97
	v_max_f32_e32 v2, v96, v96
	v_max_f32_e32 v0, v2, v0
	v_max3_f32 v2, v98, v99, v81
	v_max3_f32 v0, v0, v80, v82
	v_max3_f32 v0, v0, v83, v100
	v_max3_f32 v2, v2, v102, v103
	v_max3_f32 v0, v0, v101, v84
	v_max3_f32 v2, v2, v86, v87
	v_max3_f32 v0, v0, v85, v104
	v_max3_f32 v2, v2, v106, v107
	v_max3_f32 v0, v0, v105, v88
	v_max3_f32 v2, v2, v90, v91
	v_max3_f32 v0, v0, v89, v108
	v_max3_f32 v2, v2, v110, v111
	v_max3_f32 v0, v0, v109, v92
	v_max3_f32 v2, v2, v94, v95
	v_max3_f32 v0, v0, v93, v2
	v_mov_b32_e32 v2, v0
	s_nop 1
	v_permlane32_swap_b32_e32 v0, v2
	v_max_f32_e32 v0, v0, v2
	v_sub_f32_e32 v10, v82, v0
	s_add_i32 s4, s1, 0
	v_exp_f32_e32 v120, v10
	v_add_u32_e32 v10, s4, v128
	v_sub_f32_e32 v2, v90, v0
	v_sub_f32_e32 v3, v89, v0
	v_sub_f32_e32 v4, v88, v0
	v_sub_f32_e32 v5, v87, v0
	v_sub_f32_e32 v6, v86, v0
	v_sub_f32_e32 v7, v85, v0
	v_sub_f32_e32 v8, v84, v0
	v_sub_f32_e32 v9, v83, v0
	v_sub_f32_e32 v85, v103, v0
	v_sub_f32_e32 v86, v102, v0
	v_sub_f32_e32 v87, v101, v0
	v_sub_f32_e32 v88, v100, v0
	v_sub_f32_e32 v89, v99, v0
	v_sub_f32_e32 v90, v98, v0
	v_sub_f32_e32 v15, v97, v0
	v_sub_f32_e32 v14, v96, v0
	v_add3_u32 v192, v10, v181, v180
	v_exp_f32_e32 v14, v14
	v_exp_f32_e32 v15, v15
	v_exp_f32_e32 v118, v90
	v_exp_f32_e32 v119, v89
	v_exp_f32_e32 v121, v9
	v_exp_f32_e32 v122, v88
	v_exp_f32_e32 v124, v8
	v_exp_f32_e32 v123, v87
	v_exp_f32_e32 v125, v7
	v_exp_f32_e32 v126, v86
	v_exp_f32_e32 v130, v6
	v_exp_f32_e32 v127, v85
	ds_read_b64_tr_b16 v[6:7], v192 offset:8192
	ds_read_b64_tr_b16 v[8:9], v192 offset:9216
	v_sub_f32_e32 v11, v81, v0
	v_sub_f32_e32 v12, v80, v0
	v_sub_f32_e32 v13, v106, v0
	v_add_u32_e32 v193, v10, v182
	v_exp_f32_e32 v116, v12
	v_exp_f32_e32 v117, v11
	v_exp_f32_e32 v136, v13
	ds_read_b64_tr_b16 v[10:11], v193 offset:8192
	ds_read_b64_tr_b16 v[12:13], v193 offset:9216
	ds_read_b64_tr_b16 v[112:113], v192 offset:10240
	ds_read_b64_tr_b16 v[114:115], v192 offset:11264
	v_sub_f32_e32 v92, v92, v0
	v_sub_f32_e32 v91, v91, v0
	v_sub_f32_e32 v80, v109, v0
	v_sub_f32_e32 v81, v108, v0
	v_sub_f32_e32 v82, v107, v0
	v_sub_f32_e32 v83, v105, v0
	v_sub_f32_e32 v84, v104, v0
	v_exp_f32_e32 v131, v5
	v_exp_f32_e32 v134, v4
	v_exp_f32_e32 v135, v3
	v_exp_f32_e32 v138, v2
	v_cvt_pk_bf16_f32 v2, v14, v15
	v_cvt_pk_bf16_f32 v3, v118, v119
	v_cvt_pk_bf16_f32 v4, v122, v123
	v_cvt_pk_bf16_f32 v5, v126, v127
	v_sub_f32_e32 v166, v95, v0
	v_sub_f32_e32 v189, v94, v0
	v_sub_f32_e32 v141, v93, v0
	v_sub_f32_e32 v143, v111, v0
	v_sub_f32_e32 v142, v110, v0
	v_exp_f32_e32 v132, v84
	v_exp_f32_e32 v133, v83
	s_waitcnt lgkmcnt(4)
	v_mfma_f32_32x32x16_bf16 v[96:111], v[6:9], v[2:5], 0
	v_exp_f32_e32 v137, v82
	v_exp_f32_e32 v139, v91
	v_exp_f32_e32 v128, v81
	v_exp_f32_e32 v140, v92
	v_exp_f32_e32 v129, v80
	ds_read_b64_tr_b16 v[6:7], v193 offset:10240
	ds_read_b64_tr_b16 v[8:9], v193 offset:11264
	v_exp_f32_e32 v142, v142
	s_waitcnt lgkmcnt(4)
	v_mfma_f32_32x32x16_bf16 v[80:95], v[10:13], v[2:5], 0
	v_exp_f32_e32 v143, v143
	v_cvt_pk_bf16_f32 v2, v132, v133
	v_cvt_pk_bf16_f32 v3, v136, v137
	v_cvt_pk_bf16_f32 v4, v128, v129
	v_cvt_pk_bf16_f32 v5, v142, v143
	v_cvt_pk_bf16_f32 v10, v116, v117
	v_cvt_pk_bf16_f32 v11, v120, v121
	s_waitcnt lgkmcnt(2)
	v_mfma_f32_32x32x16_bf16 v[96:111], v[112:115], v[2:5], v[96:111]
	ds_read_b64_tr_b16 v[112:113], v192 offset:12288
	ds_read_b64_tr_b16 v[114:115], v192 offset:13312
	v_cvt_pk_bf16_f32 v12, v124, v125
	v_cvt_pk_bf16_f32 v13, v130, v131
	v_exp_f32_e32 v141, v141
	v_exp_f32_e32 v190, v189
	v_exp_f32_e32 v191, v166
	v_add_f32_e32 v14, v116, v14
	v_add_f32_e32 v15, v117, v15
	s_waitcnt lgkmcnt(2)
	v_mfma_f32_32x32x16_bf16 v[80:95], v[6:9], v[2:5], v[80:95]
	ds_read_b64_tr_b16 v[2:3], v193 offset:12288
	ds_read_b64_tr_b16 v[4:5], v193 offset:13312
	ds_read_b64_tr_b16 v[6:7], v192 offset:14336
	ds_read_b64_tr_b16 v[8:9], v192 offset:15360
	v_add_f32_e64 v116, v140, v128
	v_add_f32_e64 v117, v141, v129
	v_add_f32_e32 v136, v138, v136
	v_add_f32_e32 v137, v139, v137
	v_add_f32_e32 v118, v120, v118
	v_add_f32_e32 v119, v121, v119
	v_add_f32_e32 v120, v190, v142
	v_add_f32_e32 v121, v191, v143
	v_add_f32_e32 v126, v130, v126
	v_add_f32_e32 v127, v131, v127
	v_add_f32_e32 v130, v134, v132
	v_add_f32_e32 v131, v135, v133
	s_waitcnt lgkmcnt(4)
	v_mfma_f32_32x32x16_bf16 v[96:111], v[112:115], v[10:13], v[96:111]
	ds_read_b64_tr_b16 v[112:113], v193 offset:14336
	ds_read_b64_tr_b16 v[114:115], v193 offset:15360
	s_waitcnt vmcnt(2) lgkmcnt(0)
	s_barrier
	s_andn2_b64 vcc, exec, s[60:61]
	s_waitcnt lgkmcnt(4)
	v_mfma_f32_32x32x16_bf16 v[80:95], v[2:5], v[10:13], v[80:95]
	v_add_f32_e64 v2, v124, v122
	v_add_f32_e64 v3, v125, v123
	v_cvt_pk_bf16_f32 v4, v140, v141
	v_add_f32_e64 v10, v2, v116
	v_add_f32_e64 v11, v3, v117
	v_cvt_pk_bf16_f32 v2, v134, v135
	v_cvt_pk_bf16_f32 v3, v138, v139
	v_cvt_pk_bf16_f32 v5, v190, v191
	v_add_f32_e32 v12, v14, v130
	v_add_f32_e32 v13, v15, v131
	s_waitcnt lgkmcnt(2)
	v_mfma_f32_32x32x16_bf16 v[96:111], v[6:9], v[2:5], v[96:111]
	v_add_f32_e64 v6, v126, v120
	v_add_f32_e64 v7, v127, v121
	v_add_f32_e64 v8, v118, v136
	v_add_f32_e64 v9, v119, v137
	v_add_f32_e64 v6, v8, v6
	v_add_f32_e64 v7, v9, v7
	v_add_f32_e32 v8, v12, v10
	v_add_f32_e32 v9, v13, v11
	s_nop 0
	v_add_f32_e32 v6, v8, v6
	v_add_f32_e32 v7, v9, v7
	s_waitcnt lgkmcnt(0)
	v_mfma_f32_32x32x16_bf16 v[80:95], v[112:115], v[2:5], v[80:95]
	v_add_f32_e32 v6, v6, v7
	v_add_f32_e32 v166, 0, v6
	s_cbranch_vccnz .LBB0_884
	s_and_b32 s0, s12, s0
	s_and_b64 s[4:5], s[6:7], exec
	s_cselect_b32 s4, -1, s11
	v_add_f32_e32 v0, 0, v0

.LBB0_985:
	v_add_u32_e32 v10, s51, v188
	v_add3_u32 v189, v10, v181, v180
	v_add_u32_e32 v192, v10, v182
	ds_read_b64_tr_b16 v[6:7], v189 offset:8192
	ds_read_b64_tr_b16 v[8:9], v189 offset:9216
	ds_read_b64_tr_b16 v[10:11], v192 offset:8192
	ds_read_b64_tr_b16 v[12:13], v192 offset:9216
	s_nop 2
	v_max_f32_e32 v2, v129, v129
	v_max_f32_e32 v3, v128, v128
	v_max_f32_e32 v2, v3, v2
	v_max3_f32 v3, v130, v131, v113
	v_max3_f32 v2, v2, v112, v114
	v_max3_f32 v2, v2, v115, v132
	v_max3_f32 v3, v3, v134, v135
	v_max3_f32 v2, v2, v133, v116
	v_max3_f32 v3, v3, v118, v119
	v_max3_f32 v2, v2, v117, v136
	v_max3_f32 v3, v3, v138, v139
	v_max3_f32 v2, v2, v137, v120
	v_max3_f32 v3, v3, v122, v123
	v_max3_f32 v2, v2, v121, v140
	v_max3_f32 v3, v3, v142, v143
	v_max3_f32 v2, v2, v141, v124
	v_max3_f32 v3, v3, v126, v127
	v_max3_f32 v2, v2, v125, v3
	v_mov_b32_e32 v3, v2
	s_nop 1
	v_permlane32_swap_b32_e32 v2, v3
	v_max_f32_e32 v2, v2, v3
	v_cmp_lt_f32_e32 vcc, s91, v2
	s_cbranch_vccz .LBB0_987
	s_nop 0
	v_cndmask_b32_e32 v3, 0, v2, vcc
	v_exp_f32_e64 v2, -v3
	v_sub_f32_e32 v127, v127, v3
	v_sub_f32_e32 v126, v126, v3
	v_sub_f32_e32 v125, v125, v3
	v_sub_f32_e32 v124, v124, v3
	v_sub_f32_e32 v123, v123, v3
	v_sub_f32_e32 v122, v122, v3
	v_sub_f32_e32 v121, v121, v3
	v_sub_f32_e32 v120, v120, v3
	v_sub_f32_e32 v119, v119, v3
	v_sub_f32_e32 v118, v118, v3
	v_sub_f32_e32 v117, v117, v3
	v_sub_f32_e32 v116, v116, v3
	v_sub_f32_e32 v115, v115, v3
	v_sub_f32_e32 v114, v114, v3
	v_sub_f32_e32 v113, v113, v3
	v_sub_f32_e32 v112, v112, v3
	v_sub_f32_e32 v143, v143, v3
	v_sub_f32_e32 v142, v142, v3
	v_sub_f32_e32 v141, v141, v3
	v_sub_f32_e32 v140, v140, v3
	v_sub_f32_e32 v139, v139, v3
	v_sub_f32_e32 v138, v138, v3
	v_sub_f32_e32 v137, v137, v3
	v_sub_f32_e32 v136, v136, v3
	v_sub_f32_e32 v135, v135, v3
	v_sub_f32_e32 v134, v134, v3
	v_sub_f32_e32 v133, v133, v3
	v_sub_f32_e32 v132, v132, v3
	v_sub_f32_e32 v131, v131, v3
	v_sub_f32_e32 v130, v130, v3
	v_sub_f32_e32 v129, v129, v3
	v_sub_f32_e32 v128, v128, v3
	v_add_f32_e32 v0, v0, v3
	v_mul_f32_e32 v166, v166, v2
	v_mul_f32_e32 v110, v110, v2
	v_mul_f32_e32 v111, v111, v2
	v_mul_f32_e32 v108, v108, v2
	v_mul_f32_e32 v109, v109, v2
	v_mul_f32_e32 v106, v106, v2
	v_mul_f32_e32 v107, v107, v2
	v_mul_f32_e32 v104, v104, v2
	v_mul_f32_e32 v105, v105, v2
	v_mul_f32_e32 v102, v102, v2
	v_mul_f32_e32 v103, v103, v2
	v_mul_f32_e32 v100, v100, v2
	v_mul_f32_e32 v101, v101, v2
	v_mul_f32_e32 v98, v98, v2
	v_mul_f32_e32 v99, v99, v2
	v_mul_f32_e32 v96, v96, v2
	v_mul_f32_e32 v97, v97, v2
	v_mul_f32_e32 v94, v94, v2
	v_mul_f32_e32 v95, v95, v2
	v_mul_f32_e32 v92, v92, v2
	v_mul_f32_e32 v93, v93, v2
	v_mul_f32_e32 v90, v90, v2
	v_mul_f32_e32 v91, v91, v2
	v_mul_f32_e32 v88, v88, v2
	v_mul_f32_e32 v89, v89, v2
	v_mul_f32_e32 v86, v86, v2
	v_mul_f32_e32 v87, v87, v2
	v_mul_f32_e32 v84, v84, v2
	v_mul_f32_e32 v85, v85, v2
	v_mul_f32_e32 v82, v82, v2
	v_mul_f32_e32 v83, v83, v2
	v_mul_f32_e32 v80, v80, v2
	v_mul_f32_e32 v81, v81, v2
